# hand-rewritten rowpass_res loops (batched loads, preloaded norm gains, DPP reduce), mixer prefetch no longer drained, npt=52
# speedup vs baseline: 1.0264x; 1.0264x over previous
;     __host__ __device__ bool next(int i, Unit& u) const { if (i >= nu) return false; u.pm = 16 * x + (s >> 1); u.pn = pn0 + nu * (s & 1) + i; return true; }
;     __host__ __device__ bool next(int i, Unit& u) const { if (!StaticOrder::next(i, u)) return false; u.pn += pn0; return true; }
;     __host__ __device__ bool next(int i, Unit& u) const {
;         const long L = (long)i * G + c; if (L >= nwg) return false;
;         int wgid = (int)L; { const int q = nwg / NXCD, r = nwg % NXCD, xcd = wgid % NXCD, off = wgid / NXCD; wgid = (xcd < r ? xcd * (q + 1) : r * (q + 1) + (xcd - r) * q) + off; }
;         const int nig = WGM * nN, gid = wgid / nig, fm = gid * WGM, gsz = (nM - fm) < WGM ? (nM - fm) : WGM;
;         u.pm = fm + ((wgid % nig) % gsz); u.pn = (wgid % nig) / gsz; return true;
; __global__ void __launch_bounds__(NTHREADS, 2) fwd_megakernel(Params p) {
;     ...
;             pg8::Gemm g{A, (const bf16*)(ws + WS_WIN), MF, NIN, D}; pg8::StaticOrder S; int npt_ = 48; asm volatile("" : "+s"(npt_)); S.init(MF, npt_ * 256, F.G, F.bx);
.LBB0_124:
	v_readlane_b32 s0, v254, 18
	v_mbcnt_lo_u32_b32 v0, -1, 0
	v_mbcnt_hi_u32_b32 v0, -1, v0
	v_readlane_b32 s66, v254, 19
	s_mov_b32 s2, s53
	v_add_u32_e32 v203, s0, v0
	s_mov_b32 s16, 52
	s_lshl_b32 s24, s16, 6
	v_mov_b32_e32 v8, v203
	s_cmp_lt_i32 s66, s24
	s_mov_b32 s79, 0x10000
	v_readfirstlane_b32 s67, v203
	s_cselect_b64 s[0:1], -1, 0
	s_cmp_ge_i32 s66, s24
	v_readfirstlane_b32 s3, v8
	s_cbranch_scc1 .LBB0_126
	s_lshl_b32 s4, s16, 3
	s_abs_i32 s7, s4
	v_cvt_f32_u32_e32 v0, s7
	s_ashr_i32 s5, s66, 31
	s_lshr_b32 s5, s5, 29
	s_add_i32 s5, s66, s5
	v_rcp_iflag_f32_e32 v0, v0
	s_ashr_i32 s6, s5, 3
	s_and_b32 s5, s5, -8
	s_sub_i32 s5, s66, s5
	v_mul_f32_e32 v0, 0x4f7ffffe, v0
	v_cvt_u32_f32_e32 v0, v0
	s_lshr_b32 s8, s5, 31
	s_or_b32 s8, s4, s8
	s_sub_i32 s9, 0, s7
	v_readfirstlane_b32 s10, v0
	s_mul_i32 s5, s8, s5
	s_mul_i32 s9, s9, s10
	s_add_i32 s5, s5, s6
	s_mul_hi_u32 s9, s10, s9
	s_abs_i32 s8, s5
	s_add_i32 s10, s10, s9
	s_mul_hi_u32 s9, s8, s10
	s_mul_i32 s10, s9, s7
	s_xor_b32 s6, s5, s4
	s_sub_i32 s8, s8, s10
	s_ashr_i32 s6, s6, 31
	s_add_i32 s10, s9, 1
	s_sub_i32 s11, s8, s7
	s_cmp_ge_u32 s8, s7
	s_cselect_b32 s9, s10, s9
	s_cselect_b32 s8, s11, s8
	s_add_i32 s10, s9, 1
	s_cmp_ge_u32 s8, s7
	s_cselect_b32 s7, s10, s9
	s_xor_b32 s7, s7, s6
	s_sub_i32 s6, s7, s6
	s_lshl_b32 s7, s6, 3
	s_sub_i32 s8, 64, s7
	s_min_i32 s8, s8, 8
	s_abs_i32 s9, s8
	v_cvt_f32_u32_e32 v0, s9
	s_sub_i32 s10, 0, s9
	s_mul_i32 s6, s6, s4
	s_sub_i32 s4, s5, s6
	v_rcp_iflag_f32_e32 v0, v0
	s_abs_i32 s6, s4
	s_xor_b32 s5, s4, s8
	s_ashr_i32 s5, s5, 31
	v_mul_f32_e32 v0, 0x4f7ffffe, v0
	v_cvt_u32_f32_e32 v0, v0
	s_nop 0
	v_readfirstlane_b32 s11, v0
	s_mul_i32 s10, s10, s11
	s_mul_hi_u32 s10, s11, s10
	s_add_i32 s11, s11, s10
	s_mul_hi_u32 s10, s6, s11
	s_mul_i32 s11, s10, s9
	s_sub_i32 s6, s6, s11
	s_add_i32 s11, s10, 1
	s_sub_i32 s12, s6, s9
	s_cmp_ge_u32 s6, s9
	s_cselect_b32 s10, s11, s10
	s_cselect_b32 s6, s12, s6
	s_add_i32 s11, s10, 1
	s_cmp_ge_u32 s6, s9
	s_cselect_b32 s6, s11, s10
	s_xor_b32 s6, s6, s5
	s_sub_i32 s36, s6, s5
	s_mul_i32 s5, s36, s8
	s_sub_i32 s4, s4, s5
	s_add_i32 s90, s4, s7

; __device__ __forceinline__ int mx_row(int b, int c, int t, bool& valid) { if (c == 0) { valid = t >= 16; return MF + t - 16; } valid = true; return b * SEQ + 32 * (c - 1) + t; }
; template <int TYPE> __device__ __forceinline__ void mixer_mfma_unit(const Frame& F, const Params& p, const unsigned char* ws, int b, int h, const float* hgw) {
;     ...
;         bool ovalid; const int orow = mx_row(b, c, ot, ovalid);
;         u32x4 g0 = {0u, 0u, 0u, 0u}, g1 = {0u, 0u, 0u, 0u};
;         const unsigned oo = ((unsigned)orow * 2048u + (unsigned)(h * 256 + oe0)) * 2u;
;         if (ovalid) { const unsigned go = (unsigned)(TYPE == 0 ? WS_RG : WS_HG) + oo; g0 = *(const u32x4*)(ws + go); g1 = *(const u32x4*)(ws + go + 16u); }
.LBB0_360:
	s_cmp_lg_u32 s66, 0
	s_cselect_b64 vcc, -1, 0
	v_cndmask_b32_e32 v64, v188, v137, vcc
	s_or_b64 s[96:97], s[8:9], vcc
	v_lshl_or_b32 v139, v64, 12, v138
	v_mov_b32_e32 v122, 0
	v_mov_b32_e32 v123, 0
	v_mov_b32_e32 v124, 0
	v_mov_b32_e32 v125, 0
	v_mov_b32_e32 v118, 0
	v_mov_b32_e32 v119, 0
	v_mov_b32_e32 v120, 0
	v_mov_b32_e32 v121, 0
	s_and_saveexec_b64 s[64:65], s[96:97]
	s_cbranch_execz .LBB0_362
	v_add_u32_e32 v64, 0x24480000, v139
	global_load_dwordx4 v[122:125], v64, s[94:95] offset:16
	global_load_dwordx4 v[118:121], v64, s[94:95]

; __device__ __forceinline__ int mx_row(int b, int c, int t, bool& valid) { if (c == 0) { valid = t >= 16; return MF + t - 16; } valid = true; return b * SEQ + 32 * (c - 1) + t; }
; template <int TYPE> __device__ __forceinline__ void mixer_mfma_unit(const Frame& F, const Params& p, const unsigned char* ws, int b, int h, const float* hgw) {
;     ...
;         bool ovalid; const int orow = mx_row(b, c, ot, ovalid);
;         u32x4 g0 = {0u, 0u, 0u, 0u}, g1 = {0u, 0u, 0u, 0u};
;         const unsigned oo = ((unsigned)orow * 2048u + (unsigned)(h * 256 + oe0)) * 2u;
;         if (ovalid) { const unsigned go = (unsigned)(TYPE == 0 ? WS_RG : WS_HG) + oo; g0 = *(const u32x4*)(ws + go); g1 = *(const u32x4*)(ws + go + 16u); }
.LBB0_387:
	s_cmp_lg_u32 s96, 0
	s_cselect_b64 vcc, -1, 0
	v_cndmask_b32_e32 v64, v188, v217, vcc
	s_or_b64 s[64:65], s[8:9], vcc
	v_lshl_or_b32 v221, v64, 12, v220
	v_mov_b32_e32 v134, 0
	v_mov_b32_e32 v135, 0
	v_mov_b32_e32 v136, 0
	v_mov_b32_e32 v137, 0
	v_mov_b32_e32 v130, 0
	v_mov_b32_e32 v131, 0
	v_mov_b32_e32 v132, 0
	v_mov_b32_e32 v133, 0
	s_and_saveexec_b64 s[66:67], s[64:65]
	s_cbranch_execz .LBB0_389
	v_add_u32_e32 v64, 0x16100000, v221
	global_load_dwordx4 v[134:137], v64, s[94:95] offset:16
	global_load_dwordx4 v[130:133], v64, s[94:95]

;     __host__ __device__ bool next(int i, Unit& u) const { if (i >= nu) return false; u.pm = 16 * x + (s >> 1); u.pn = pn0 + nu * (s & 1) + i; return true; }
;     __host__ __device__ bool next(int i, Unit& u) const { if (!StaticOrder::next(i, u)) return false; u.pn += pn0; return true; }
;     __host__ __device__ bool next(int i, Unit& u) const {
;         const long L = (long)i * G + c; if (L >= nwg) return false;
;         int wgid = (int)L; { const int q = nwg / NXCD, r = nwg % NXCD, xcd = wgid % NXCD, off = wgid / NXCD; wgid = (xcd < r ? xcd * (q + 1) : r * (q + 1) + (xcd - r) * q) + off; }
;         const int nig = WGM * nN, gid = wgid / nig, fm = gid * WGM, gsz = (nM - fm) < WGM ? (nM - fm) : WGM;
;         u.pm = fm + ((wgid % nig) % gsz); u.pn = (wgid % nig) / gsz; return true;
; __global__ void __launch_bounds__(NTHREADS, 2) fwd_megakernel(Params p) {
;     ...
;                   pg8::Gemm g{A, (const bf16*)(ws + WS_WIN), MF, NIN, D}; pg8::OffsetOrder S; int npt_ = 48; asm volatile("" : "+s"(npt_)); S.init(MF, (64 - npt_) * 256, F.G, F.bx); S.pn0 = npt_;
.LBB0_391:
	v_readlane_b32 s0, v254, 50
	v_readlane_b32 s1, v254, 51
	s_andn2_b64 vcc, exec, s[0:1]
	v_readlane_b32 s78, v255, 22
	s_cbranch_vccnz .LBB0_446
	s_mov_b32 s52, 52
	s_lshl_b32 s0, s52, 8
	s_sub_i32 s3, 0x4000, s0
	s_ashr_i32 s2, s3, 2
	v_mov_b32_e32 v8, v203
	s_cmp_lt_i32 s71, s2
	s_cselect_b64 s[0:1], -1, 0
	s_cmp_ge_i32 s71, s2
	v_readfirstlane_b32 s16, v8
	s_cbranch_scc1 .LBB0_394
	s_ashr_i32 s4, s3, 5
	s_abs_i32 s7, s4
	v_cvt_f32_u32_e32 v0, s7
	s_ashr_i32 s5, s71, 31
	s_lshr_b32 s5, s5, 29
	s_add_i32 s5, s71, s5
	v_rcp_iflag_f32_e32 v0, v0
	s_ashr_i32 s6, s5, 3
	s_and_b32 s5, s5, -8
	s_sub_i32 s5, s71, s5
	v_mul_f32_e32 v0, 0x4f7ffffe, v0
	v_cvt_u32_f32_e32 v0, v0
	s_lshr_b32 s8, s5, 31
	s_or_b32 s8, s4, s8
	s_sub_i32 s9, 0, s7
	v_readfirstlane_b32 s10, v0
	s_mul_i32 s5, s8, s5
	s_mul_i32 s9, s9, s10
	s_add_i32 s5, s5, s6
	s_mul_hi_u32 s9, s10, s9
	s_abs_i32 s8, s5
	s_add_i32 s10, s10, s9
	s_mul_hi_u32 s9, s8, s10
	s_mul_i32 s10, s9, s7
	s_xor_b32 s6, s5, s4
	s_sub_i32 s8, s8, s10
	s_ashr_i32 s6, s6, 31
	s_add_i32 s10, s9, 1
	s_sub_i32 s11, s8, s7
	s_cmp_ge_u32 s8, s7
	s_cselect_b32 s9, s10, s9
	s_cselect_b32 s8, s11, s8
	s_add_i32 s10, s9, 1
	s_cmp_ge_u32 s8, s7
	s_cselect_b32 s7, s10, s9
	s_xor_b32 s7, s7, s6
	s_sub_i32 s6, s7, s6
	s_lshl_b32 s7, s6, 3
	s_sub_i32 s8, 64, s7
	s_min_i32 s8, s8, 8
	s_abs_i32 s9, s8
	v_cvt_f32_u32_e32 v0, s9
	s_sub_i32 s10, 0, s9
	s_mul_i32 s6, s6, s4
	s_sub_i32 s4, s5, s6
	v_rcp_iflag_f32_e32 v0, v0
	s_abs_i32 s6, s4
	s_xor_b32 s5, s4, s8
	s_ashr_i32 s5, s5, 31
	v_mul_f32_e32 v0, 0x4f7ffffe, v0
	v_cvt_u32_f32_e32 v0, v0
	s_nop 0
	v_readfirstlane_b32 s11, v0
	s_mul_i32 s10, s10, s11
	s_mul_hi_u32 s10, s11, s10
	s_add_i32 s11, s11, s10
	s_mul_hi_u32 s10, s6, s11
	s_mul_i32 s11, s10, s9
	s_sub_i32 s6, s6, s11
	s_add_i32 s11, s10, 1
	s_sub_i32 s12, s6, s9
	s_cmp_ge_u32 s6, s9
	s_cselect_b32 s10, s11, s10
	s_cselect_b32 s6, s12, s6
	s_add_i32 s11, s10, 1
	s_cmp_ge_u32 s6, s9
	s_cselect_b32 s6, s11, s10
	s_xor_b32 s6, s6, s5
	s_sub_i32 s5, s6, s5
	s_mul_i32 s6, s5, s8
	s_sub_i32 s4, s4, s6
	s_add_i32 s42, s4, s7
	s_add_i32 s28, s5, s52

;     __host__ __device__ bool next(int i, Unit& u) const { if (i >= nu) return false; u.pm = 16 * x + (s >> 1); u.pn = pn0 + nu * (s & 1) + i; return true; }
;     __host__ __device__ bool next(int i, Unit& u) const { if (!StaticOrder::next(i, u)) return false; u.pn += pn0; return true; }
; #define PG8_WAIT_V(n) asm volatile("s_waitcnt vmcnt(" #n ")" ::: "memory")
; template <class Epi, class Sched, bool ALIGN_EPI = false, bool SP2 = false>
; __device__ __forceinline__ void gemm_phase(PG8_LAS unsigned char* lds, const Gemm g, const Sched& S, const Epi& E, int tid_in) {
;     ...
;     for (int i = 0; i < 2; ++i) { int R, C; stage_rc(tid * 16 + i * 8192, R, C); const int Rb = Epi::PERM ? ((R & ~31) + perm32(R & 31)) : R;
;         voffA[i] = (unsigned)(R * K + C) * 2u; voffB[i] = (unsigned)(Rb * K + C) * 2u; }
;     const size_t kstep = (size_t)(BK * 2);
;     const size_t hstep = (size_t)HALF * K * 2;
;     const size_t tstep = 2 * hstep;
;     const unsigned ldsw = (unsigned)wid * 1024u;
;     const int aoff = lds_byte(wr * 64 + fr, fq * 8), boff = lds_byte(wc * 32 + fr, fq * 8);
;     ...
;     Unit cur, nxt; int ui = 0;
;     if (!S.next(0, cur)) return;
;     f32x4 acc[2][2][4][2];
; #pragma unroll
;     for (int a = 0; a < 2; ++a)
; #pragma unroll
;         for (int b = 0; b < 2; ++b)
; #pragma unroll
;             for (int m = 0; m < 4; ++m)
; #pragma unroll
;                 for (int n = 0; n < 2; ++n) acc[a][b][m][n] = (f32x4){0.f, 0.f, 0.f, 0.f};
;     bf16x8 At[4][2], B0[2][2], B1[2][2];
;     const char* cA = (const char*)g.A + (size_t)cur.pm * tstep; const char* cB = (const char*)g.Bt + (size_t)cur.pn * tstep;
;     S.a_ready(cur);
;     if constexpr (SP2) {
;         PG8_STAGE(PG8_SB(0, 0), cB, voffB); PG8_STAGE(PG8_SB(0, 1), cB + hstep, voffB); PG8_STAGE(PG8_SA(0, 0), cA, voffA); PG8_STAGE(PG8_SA(0, 1), cA + hstep, voffA);
;         if (wr == 1) PG8_BAR;
;         PG8_WAIT_V(2); PG8_BAR;
;         PG8_STAGE(PG8_SB(1, 0), cB + kstep, voffB); PG8_STAGE(PG8_SA(1, 0), cA + kstep, voffA); PG8_STAGE(PG8_SB(1, 1), cB + hstep + kstep, voffB);
; __global__ void __launch_bounds__(NTHREADS, 2) fwd_megakernel(Params p) {
;     ...
;               pg8::Gemm g{A, (const bf16*)(ws + WS_WIN), MF, NIN, D}; int npt_ = 48; asm volatile("" : "+s"(npt_)); pg8::XcdPanelOrder S; S.x = F.bx & 7; S.s = F.bx >> 3; S.pn0 = npt_; S.nu = (64 - npt_) >> 1;
.LBB0_447:
	s_and_b64 vcc, exec, s[0:1]
	s_mov_b32 s79, 0x1c000
	s_cbranch_vccz .LBB0_498
	s_mov_b32 s1, 52
	s_sub_i32 s0, 64, s1
	s_ashr_i32 s46, s0, 1
	s_cmp_lt_i32 s46, 1
	v_readfirstlane_b32 s34, v203
	s_cbranch_scc1 .LBB0_498
	v_lshlrev_b32_e32 v0, 4, v203
	v_add_u32_e32 v1, 0x2000, v0
	v_ashrrev_i32_e32 v2, 31, v1
	v_lshrrev_b32_e32 v2, 22, v2
	v_add_u32_e32 v2, v1, v2
	v_ashrrev_i32_e32 v8, 10, v2
	v_mul_i32_i24_e32 v2, 0x400, v8
	v_sub_u32_e32 v1, v1, v2
	v_lshrrev_b32_e32 v2, 4, v1
	v_bitop3_b32 v1, v2, v1, 32 bitop3:0x6c
	s_add_u32 s47, s94, 0x400000
	v_ashrrev_i32_e32 v2, 31, v1
	s_addc_u32 s52, s95, 0
	s_lshl_b32 s0, s71, 4
	v_lshrrev_b32_e32 v2, 26, v2
	s_and_b32 s0, s0, 48
	s_ashr_i32 s2, s71, 4
	v_add_u32_e32 v2, v1, v2
	v_lshlrev_b32_e32 v3, 3, v8
	s_add_i32 s0, s0, s2
	s_bfe_i32 s2, s71, 0x10003
	v_ashrrev_i32_e32 v9, 6, v2
	v_and_b32_e32 v3, -16, v3
	s_and_b32 s2, s2, s46
	v_add_u32_e32 v3, v9, v3
	s_add_i32 s2, s2, s1
	v_and_b32_e32 v4, 3, v9
	s_mov_b32 s1, 0xfffe0
	v_lshrrev_b32_e32 v5, 2, v3
	v_lshlrev_b32_e32 v6, 1, v3
	v_and_or_b32 v4, v3, s1, v4
	v_and_b32_e32 v5, 4, v5
	v_and_b32_e32 v6, 24, v6
	v_and_b32_e32 v2, 0xc0, v2
	v_or3_b32 v4, v4, v5, v6
	v_sub_u32_e32 v1, v1, v2
	v_mov_b32_e32 v6, 1
	v_lshlrev_b32_e32 v5, 5, v8
	v_ashrrev_i16_sdwa v1, v6, sext(v1) dst_sel:DWORD dst_unused:UNUSED_PAD src0_sel:DWORD src1_sel:BYTE_0
	v_and_b32_e32 v5, 32, v5
	v_bfe_i32 v10, v1, 0, 16
	v_add_lshl_u32 v1, v5, v10, 1
	v_lshl_add_u32 v172, v4, 12, v1
	v_lshl_add_u32 v174, v3, 12, v1
	v_bfe_i32 v1, v203, 27, 1
	v_lshrrev_b32_e32 v1, 22, v1
	v_add_u32_e32 v1, v0, v1
	v_and_b32_e32 v1, 0xfffffc00, v1
	v_sub_u32_e32 v0, v0, v1
	v_lshrrev_b32_e32 v1, 4, v0
	v_ashrrev_i32_e32 v2, 31, v203
	v_bitop3_b32 v0, v1, v0, 32 bitop3:0x6c
	v_lshrrev_b32_e32 v2, 26, v2
	v_ashrrev_i32_e32 v1, 31, v0
	v_add_u32_e32 v2, v203, v2
	v_lshrrev_b32_e32 v1, 26, v1
	v_ashrrev_i32_e32 v12, 6, v2
	v_add_u32_e32 v1, v0, v1
	v_lshlrev_b32_e32 v2, 3, v12
	v_ashrrev_i32_e32 v11, 6, v1
	v_and_b32_e32 v2, -16, v2
	v_add_u32_e32 v2, v11, v2
	v_and_b32_e32 v3, 3, v11
	v_lshrrev_b32_e32 v4, 2, v2
	v_lshlrev_b32_e32 v5, 1, v2
	v_and_b32_e32 v1, 0xc0, v1
	s_ashr_i32 s35, s34, 6
	v_and_or_b32 v3, v2, s1, v3
	v_and_b32_e32 v4, 4, v4
	v_and_b32_e32 v5, 24, v5
	v_sub_u32_e32 v0, v0, v1
	s_ashr_i32 s1, s0, 31
	s_ashr_i32 s3, s2, 31
	s_ashr_i32 s36, s34, 8
	s_lshl_b32 s64, s35, 10
	v_or3_b32 v3, v3, v4, v5
	v_lshlrev_b32_e32 v4, 5, v12
	v_ashrrev_i16_sdwa v0, v6, sext(v0) dst_sel:DWORD dst_unused:UNUSED_PAD src0_sel:DWORD src1_sel:BYTE_0
	s_lshl_b64 s[6:7], s[0:1], 20
	s_lshl_b64 s[4:5], s[2:3], 20
	v_and_b32_e32 v4, 32, v4
	v_bfe_i32 v13, v0, 0, 16
	s_add_u32 s4, s47, s4
	v_add_lshl_u32 v0, v4, v13, 1
	s_addc_u32 s5, s52, s5
	s_add_i32 s1, s64, 0
	v_lshl_add_u32 v176, v3, 12, v0
	s_add_i32 m0, s1, 0x10000
	v_lshl_add_u32 v178, v2, 12, v0
	global_load_lds_dwordx4 v176, s[4:5]
	s_add_i32 m0, s1, 0x12000
	s_add_u32 s8, s4, 0x80000
	global_load_lds_dwordx4 v172, s[4:5]
	s_addc_u32 s9, s5, 0
	s_add_i32 m0, s1, 0x14000
	v_mov_b32_e32 v177, v97
	global_load_lds_dwordx4 v176, s[8:9]
	s_add_i32 m0, s1, 0x16000
	s_add_u32 s6, s69, s6
	s_addc_u32 s7, s70, s7
	s_add_i32 s3, s1, 0x2000
	global_load_lds_dwordx4 v172, s[8:9]
	s_mov_b32 m0, s1
	s_add_u32 s8, s6, 0x80000
	global_load_lds_dwordx4 v178, s[6:7]
	s_mov_b32 m0, s3
	s_addc_u32 s9, s7, 0
	s_add_i32 s65, s1, 0x4000
	global_load_lds_dwordx4 v174, s[6:7]
	s_mov_b32 m0, s65
	s_add_i32 s66, s1, 0x6000
	global_load_lds_dwordx4 v178, s[8:9]
	s_mov_b32 m0, s66
	v_mov_b32_e32 v173, v97
	global_load_lds_dwordx4 v174, s[8:9]
	v_mov_b32_e32 v179, v97
	v_mov_b32_e32 v175, v97
	s_cmp_eq_u32 s36, 1
	v_lshl_add_u64 v[6:7], s[4:5], 0, v[176:177]
	v_lshl_add_u64 v[4:5], s[4:5], 0, v[172:173]
	v_lshl_add_u64 v[0:1], s[6:7], 0, v[178:179]
	s_cselect_b64 s[8:9], -1, 0
	s_cmp_lg_u32 s36, 1
	v_lshl_add_u64 v[2:3], s[6:7], 0, v[174:175]
	s_cbranch_scc1 .LBB0_451
	s_barrier

; __device__ __forceinline__ float bflo(unsigned w) { return __uint_as_float(w << 16); }
; __device__ __forceinline__ float bfhi(unsigned w) { return __uint_as_float(w & 0xffff0000u); }
; __device__ __forceinline__ void rowpass_res(const Frame& F, const Params& p, const float* gpost, const float* gnext, bool first, bool last) {
;     bf16* A = (bf16*)(p.ws + WS_A); const bf16* Msrc = (const bf16*)(p.ws + WS_M); bf16* HB = (bf16*)(p.ws + WS_HB);
;     for (int r0 = 2 * F.gw; r0 < MREAL; r0 += 2 * F.ngw) {
;         f32x4 v[2][8]; float ss[2] = {0.f, 0.f};
; #pragma unroll
;         for (int u = 0; u < 2; ++u) { const bf16* ms = Msrc + (size_t)(r0 + u) * D;
; #pragma unroll
;             for (int j = 0; j < 8; ++j) { const u32x2 mw = *(const u32x2*)(ms + 4 * F.lane + 256 * j); v[u][j] = (f32x4){bflo(mw.x), bfhi(mw.x), bflo(mw.y), bfhi(mw.y)}; } }
;         f32x4 hv[2][8];
; #pragma unroll
;         for (int u = 0; u < 2; ++u) { const int r = r0 + u; const bf16* hb = HB + (size_t)r * D;
; #pragma unroll
;             for (int j = 0; j < 8; ++j) {
;                 if (first) hv[u][j] = *(const f32x4*)((r < MF ? p.x + (size_t)r * D : p.meta + (size_t)(r - MF) * D) + 4 * F.lane + 256 * j);
;                 else { const u32x2 hw = *(const u32x2*)(hb + 4 * F.lane + 256 * j); hv[u][j] = (f32x4){bflo(hw.x), bfhi(hw.x), bflo(hw.y), bfhi(hw.y)}; } } }
.LBB0_849:
	s_or_b64 exec, exec, s[0:1]
	s_waitcnt lgkmcnt(0)
	s_barrier
	v_mbcnt_lo_u32_b32 v0, -1, 0
	v_mbcnt_hi_u32_b32 v0, -1, v0
	v_readlane_b32 s0, v254, 18
	v_readlane_b32 s1, v254, 19
	s_mov_b32 s5, s53
	v_add_u32_e32 v0, s0, v0
	s_lshl_b32 s1, s1, 3
	v_readfirstlane_b32 s0, v0
	s_ashr_i32 s0, s0, 6
	s_add_i32 s0, s1, s0
	s_mov_b32 s1, s53
	s_nop 0
	v_readlane_b32 s1, v255, 49
	s_lshl_b32 s4, s1, 11
	s_cmpk_gt_i32 s0, 0x2007
	s_cbranch_scc1 .LBB0_918
	v_and_b32_e32 v1, 64, v202
	v_add_u32_e32 v1, 64, v1
	v_xor_b32_e32 v2, 1, v202
	v_cmp_lt_i32_e32 vcc, v2, v1
	s_lshl_b64 s[2:3], s[4:5], 2
	s_add_u32 s6, s56, s2
	v_cndmask_b32_e32 v2, v202, v2, vcc
	v_lshlrev_b32_e32 v65, 2, v2
	v_xor_b32_e32 v2, 2, v202
	v_cmp_lt_i32_e32 vcc, v2, v1
	s_addc_u32 s7, s57, s3
	s_add_u32 s8, s54, s2
	v_cndmask_b32_e32 v2, v202, v2, vcc
	v_lshlrev_b32_e32 v164, 2, v2
	v_xor_b32_e32 v2, 4, v202
	v_cmp_lt_i32_e32 vcc, v2, v1
	s_addc_u32 s9, s55, s3
	s_lshl_b32 s2, s0, 1
	v_cndmask_b32_e32 v2, v202, v2, vcc
	v_lshlrev_b32_e32 v165, 2, v2
	v_xor_b32_e32 v2, 8, v202
	v_cmp_lt_i32_e32 vcc, v2, v1
	s_mov_b64 s[0:1], 0x1000
	s_ashr_i32 s3, s2, 31
	v_cndmask_b32_e32 v2, v202, v2, vcc
	v_lshlrev_b32_e32 v172, 2, v2
	v_xor_b32_e32 v2, 16, v202
	v_cmp_lt_i32_e32 vcc, v2, v1
	s_mov_b64 s[10:11], 0x1800
	s_mov_b64 s[12:13], 0x1c00
	v_cndmask_b32_e32 v2, v202, v2, vcc
	v_lshlrev_b32_e32 v173, 2, v2
	v_xor_b32_e32 v2, 32, v202
	v_cmp_lt_i32_e32 vcc, v2, v1
	s_nop 1
	v_cndmask_b32_e32 v1, v202, v2, vcc
	v_lshlrev_b32_e32 v174, 2, v1
	v_lshlrev_b32_e32 v1, 2, v0
	v_and_b32_e32 v64, 0xfc, v1
	v_lshlrev_b32_e32 v96, 2, v64
	v_lshl_add_u64 v[66:67], s[8:9], 0, v[96:97]
	v_lshl_add_u64 v[76:77], s[6:7], 0, v[96:97]
	v_lshl_add_u64 v[68:69], v[66:67], 0, s[0:1]
	v_lshl_add_u64 v[78:79], v[76:77], 0, s[0:1]
	s_lshl_b64 s[0:1], s[2:3], 12
	v_readlane_b32 s6, v255, 12
	v_and_b32_e32 v0, 63, v0
	s_add_u32 s0, s6, s0
	v_readlane_b32 s6, v255, 13
	v_lshlrev_b32_e32 v96, 3, v0
	s_addc_u32 s1, s6, s1
	v_lshl_add_u64 v[86:87], s[0:1], 0, v[96:97]
	s_lshl_b64 s[0:1], s[2:3], 13
	s_mov_b64 s[8:9], 0x1400
	s_add_u32 s3, s48, s0
	v_lshl_add_u64 v[70:71], v[66:67], 0, s[8:9]
	v_lshl_add_u64 v[72:73], v[66:67], 0, s[10:11]
	v_lshl_add_u64 v[74:75], v[66:67], 0, s[12:13]
	v_lshl_add_u64 v[80:81], v[76:77], 0, s[8:9]
	v_lshl_add_u64 v[82:83], v[76:77], 0, s[10:11]
	v_lshl_add_u64 v[84:85], v[76:77], 0, s[12:13]
	s_addc_u32 s10, s49, s1
	global_load_dwordx4 v[204:207], v[66:67], off
	global_load_dwordx4 v[208:211], v[66:67], off offset:1024
	global_load_dwordx4 v[212:215], v[66:67], off offset:2048
	global_load_dwordx4 v[216:219], v[66:67], off offset:3072
	global_load_dwordx4 v[220:223], v[68:69], off
	global_load_dwordx4 v[224:227], v[68:69], off offset:1024
	global_load_dwordx4 v[228:231], v[68:69], off offset:2048
	global_load_dwordx4 v[232:235], v[68:69], off offset:3072
	s_cmp_lg_u64 s[36:37], 0
	s_cbranch_scc0 .Lrp6_nogn
	global_load_dwordx4 v[236:239], v[76:77], off
	global_load_dwordx4 v[240:243], v[76:77], off offset:1024
	global_load_dwordx4 v[244:247], v[76:77], off offset:2048
	global_load_dwordx4 v[248:251], v[76:77], off offset:3072
	global_load_dwordx4 v[186:189], v[78:79], off
	global_load_dwordx4 v[190:193], v[78:79], off offset:1024
	global_load_dwordx4 v[194:197], v[78:79], off offset:2048
	global_load_dwordx4 v[198:201], v[78:79], off offset:3072
.Lrp6_nogn:
	s_branch .LBB0_852
.LBB0_851:
	s_add_i32 s2, s2, s22
	s_add_u32 s3, s3, s60
	v_readlane_b32 s0, v255, 14
	s_addc_u32 s10, s10, s61
	v_readlane_b32 s1, v255, 15
	s_cmpk_lt_i32 s2, 0x4010
	s_nop 0
	v_lshl_add_u64 v[86:87], v[86:87], 0, s[0:1]
	s_cbranch_scc0 .LBB0_918
.LBB0_852:
	v_add_co_u32_e32 v88, vcc, 0xfffff000, v86
	s_nop 1
	v_addc_co_u32_e32 v89, vcc, -1, v87, vcc
	v_add_co_u32_e32 v92, vcc, 0xe1880000, v86
	s_nop 1
	v_addc_co_u32_e32 v93, vcc, -1, v87, vcc
	v_add_co_u32_e32 v90, vcc, 0xe1880000, v88
	s_nop 1
	v_addc_co_u32_e32 v91, vcc, -1, v89, vcc
	global_load_dwordx2 v[98:99], v[90:91], off offset:-3584
	global_load_dwordx2 v[100:101], v[90:91], off offset:-3072
	global_load_dwordx2 v[102:103], v[90:91], off offset:-2560
	global_load_dwordx2 v[104:105], v[90:91], off offset:-2048
	global_load_dwordx2 v[106:107], v[90:91], off offset:-1536
	global_load_dwordx2 v[108:109], v[90:91], off offset:-1024
	global_load_dwordx2 v[110:111], v[90:91], off offset:-512
	global_load_dwordx2 v[112:113], v[90:91], off
	global_load_dwordx2 v[114:115], v[92:93], off offset:-3584
	global_load_dwordx2 v[116:117], v[92:93], off offset:-3072
	global_load_dwordx2 v[118:119], v[92:93], off offset:-2560
	global_load_dwordx2 v[120:121], v[92:93], off offset:-2048
	global_load_dwordx2 v[122:123], v[92:93], off offset:-1536
	global_load_dwordx2 v[124:125], v[92:93], off offset:-1024
	global_load_dwordx2 v[126:127], v[92:93], off offset:-512
	global_load_dwordx2 v[128:129], v[92:93], off
	s_cmp_lg_u64 s[92:93], 0
	s_cbranch_scc1 .Lrp6_hb
	s_cmpk_lt_i32 s2, 0x4000
	s_cbranch_scc1 .Lrp6_x
	s_add_i32 s6, s2, 0xffffc000
	s_lshl_b32 s6, s6, 13
	s_add_u32 s0, s50, s6
	s_addc_u32 s1, s51, 0
	s_branch .Lrp6_xl
.Lrp6_x:
	s_mov_b32 s0, s3
	s_mov_b32 s1, s10
; __device__ __forceinline__ float bflo(unsigned w) { return __uint_as_float(w << 16); }
; __device__ __forceinline__ float bfhi(unsigned w) { return __uint_as_float(w & 0xffff0000u); }
; __device__ __forceinline__ void rowpass_res(const Frame& F, const Params& p, const float* gpost, const float* gnext, bool first, bool last) {
;     ...
;         for (int u = 0; u < 2; ++u) { const bf16* ms = Msrc + (size_t)(r0 + u) * D;
; #pragma unroll
;             for (int j = 0; j < 8; ++j) { const u32x2 mw = *(const u32x2*)(ms + 4 * F.lane + 256 * j); v[u][j] = (f32x4){bflo(mw.x), bfhi(mw.x), bflo(mw.y), bfhi(mw.y)}; } }
;         f32x4 hv[2][8];
; #pragma unroll
;         for (int u = 0; u < 2; ++u) { const int r = r0 + u; const bf16* hb = HB + (size_t)r * D;
; #pragma unroll
;             for (int j = 0; j < 8; ++j) {
;                 if (first) hv[u][j] = *(const f32x4*)((r < MF ? p.x + (size_t)r * D : p.meta + (size_t)(r - MF) * D) + 4 * F.lane + 256 * j);
;                 else { const u32x2 hw = *(const u32x2*)(hb + 4 * F.lane + 256 * j); hv[u][j] = (f32x4){bflo(hw.x), bfhi(hw.x), bflo(hw.y), bfhi(hw.y)}; } } }
; #pragma unroll
;         for (int u = 0; u < 2; ++u)
; #pragma unroll
;             for (int j = 0; j < 8; ++j) ss[u] += (v[u][j].x * v[u][j].x + v[u][j].y * v[u][j].y) + (v[u][j].z * v[u][j].z + v[u][j].w * v[u][j].w);
.Lrp6_xl:
	s_add_u32 s8, s0, 0x2000
	s_addc_u32 s9, s1, 0
	v_lshlrev_b32_e32 v150, 4, v202
	v_add_u32_e32 v151, 0x1000, v150
	global_load_dwordx4 v[0:3], v150, s[0:1]
	global_load_dwordx4 v[4:7], v150, s[0:1] offset:1024
	global_load_dwordx4 v[8:11], v150, s[0:1] offset:2048
	global_load_dwordx4 v[12:15], v150, s[0:1] offset:3072
	global_load_dwordx4 v[16:19], v151, s[0:1]
	global_load_dwordx4 v[20:23], v151, s[0:1] offset:1024
	global_load_dwordx4 v[24:27], v151, s[0:1] offset:2048
	global_load_dwordx4 v[28:31], v151, s[0:1] offset:3072
	global_load_dwordx4 v[32:35], v150, s[8:9]
	global_load_dwordx4 v[36:39], v150, s[8:9] offset:1024
	global_load_dwordx4 v[40:43], v150, s[8:9] offset:2048
	global_load_dwordx4 v[44:47], v150, s[8:9] offset:3072
	global_load_dwordx4 v[48:51], v151, s[8:9]
	global_load_dwordx4 v[52:55], v151, s[8:9] offset:1024
	global_load_dwordx4 v[56:59], v151, s[8:9] offset:2048
	global_load_dwordx4 v[60:63], v151, s[8:9] offset:3072
	s_branch .Lrp6_ld_done
.Lrp6_hb:
	global_load_dwordx2 v[2:3], v[88:89], off offset:-3584
	global_load_dwordx2 v[6:7], v[88:89], off offset:-3072
	global_load_dwordx2 v[10:11], v[88:89], off offset:-2560
	global_load_dwordx2 v[14:15], v[88:89], off offset:-2048
	global_load_dwordx2 v[18:19], v[88:89], off offset:-1536
	global_load_dwordx2 v[22:23], v[88:89], off offset:-1024
	global_load_dwordx2 v[26:27], v[88:89], off offset:-512
	global_load_dwordx2 v[30:31], v[88:89], off
	global_load_dwordx2 v[34:35], v[86:87], off offset:-3584
	global_load_dwordx2 v[38:39], v[86:87], off offset:-3072
	global_load_dwordx2 v[42:43], v[86:87], off offset:-2560
	global_load_dwordx2 v[46:47], v[86:87], off offset:-2048
	global_load_dwordx2 v[50:51], v[86:87], off offset:-1536
	global_load_dwordx2 v[54:55], v[86:87], off offset:-1024
	global_load_dwordx2 v[58:59], v[86:87], off offset:-512
	global_load_dwordx2 v[62:63], v[86:87], off
.Lrp6_ld_done:
	s_waitcnt vmcnt(16)
	v_lshlrev_b32_e32 v130, 16, v98
	v_and_b32_e32 v131, 0xffff0000, v98
	v_lshlrev_b32_e32 v132, 16, v99
	v_and_b32_e32 v133, 0xffff0000, v99
	v_pk_mul_f32 v[94:95], v[130:131], v[130:131]
	v_pk_mul_f32 v[138:139], v[132:133], v[132:133]
	v_lshlrev_b32_e32 v134, 16, v114
	v_and_b32_e32 v135, 0xffff0000, v114
	v_lshlrev_b32_e32 v136, 16, v115
	v_and_b32_e32 v137, 0xffff0000, v115
	v_pk_mul_f32 v[140:141], v[134:135], v[134:135]
	v_pk_mul_f32 v[142:143], v[136:137], v[136:137]
	v_lshlrev_b32_e32 v130, 16, v100
	v_and_b32_e32 v131, 0xffff0000, v100
	v_lshlrev_b32_e32 v132, 16, v101
	v_and_b32_e32 v133, 0xffff0000, v101
	v_pk_fma_f32 v[94:95], v[130:131], v[130:131], v[94:95]
	v_pk_fma_f32 v[138:139], v[132:133], v[132:133], v[138:139]
	v_lshlrev_b32_e32 v134, 16, v116
	v_and_b32_e32 v135, 0xffff0000, v116
	v_lshlrev_b32_e32 v136, 16, v117
	v_and_b32_e32 v137, 0xffff0000, v117
	v_pk_fma_f32 v[140:141], v[134:135], v[134:135], v[140:141]
	v_pk_fma_f32 v[142:143], v[136:137], v[136:137], v[142:143]
	v_lshlrev_b32_e32 v130, 16, v102
	v_and_b32_e32 v131, 0xffff0000, v102
	v_lshlrev_b32_e32 v132, 16, v103
	v_and_b32_e32 v133, 0xffff0000, v103
	v_pk_fma_f32 v[94:95], v[130:131], v[130:131], v[94:95]
	v_pk_fma_f32 v[138:139], v[132:133], v[132:133], v[138:139]
	v_lshlrev_b32_e32 v134, 16, v118
	v_and_b32_e32 v135, 0xffff0000, v118
	v_lshlrev_b32_e32 v136, 16, v119
	v_and_b32_e32 v137, 0xffff0000, v119
	v_pk_fma_f32 v[140:141], v[134:135], v[134:135], v[140:141]
	v_pk_fma_f32 v[142:143], v[136:137], v[136:137], v[142:143]
	v_lshlrev_b32_e32 v130, 16, v104
	v_and_b32_e32 v131, 0xffff0000, v104
	v_lshlrev_b32_e32 v132, 16, v105
	v_and_b32_e32 v133, 0xffff0000, v105
	v_pk_fma_f32 v[94:95], v[130:131], v[130:131], v[94:95]
	v_pk_fma_f32 v[138:139], v[132:133], v[132:133], v[138:139]
	v_lshlrev_b32_e32 v134, 16, v120
	v_and_b32_e32 v135, 0xffff0000, v120
	v_lshlrev_b32_e32 v136, 16, v121
	v_and_b32_e32 v137, 0xffff0000, v121
	v_pk_fma_f32 v[140:141], v[134:135], v[134:135], v[140:141]
	v_pk_fma_f32 v[142:143], v[136:137], v[136:137], v[142:143]
	v_lshlrev_b32_e32 v130, 16, v106
	v_and_b32_e32 v131, 0xffff0000, v106
	v_lshlrev_b32_e32 v132, 16, v107
	v_and_b32_e32 v133, 0xffff0000, v107
	v_pk_fma_f32 v[94:95], v[130:131], v[130:131], v[94:95]
	v_pk_fma_f32 v[138:139], v[132:133], v[132:133], v[138:139]
	v_lshlrev_b32_e32 v134, 16, v122
	v_and_b32_e32 v135, 0xffff0000, v122
	v_lshlrev_b32_e32 v136, 16, v123
	v_and_b32_e32 v137, 0xffff0000, v123
	v_pk_fma_f32 v[140:141], v[134:135], v[134:135], v[140:141]
	v_pk_fma_f32 v[142:143], v[136:137], v[136:137], v[142:143]
	v_lshlrev_b32_e32 v130, 16, v108
	v_and_b32_e32 v131, 0xffff0000, v108
	v_lshlrev_b32_e32 v132, 16, v109
	v_and_b32_e32 v133, 0xffff0000, v109
	v_pk_fma_f32 v[94:95], v[130:131], v[130:131], v[94:95]
	v_pk_fma_f32 v[138:139], v[132:133], v[132:133], v[138:139]
	v_lshlrev_b32_e32 v134, 16, v124
	v_and_b32_e32 v135, 0xffff0000, v124
	v_lshlrev_b32_e32 v136, 16, v125
	v_and_b32_e32 v137, 0xffff0000, v125
	v_pk_fma_f32 v[140:141], v[134:135], v[134:135], v[140:141]
	v_pk_fma_f32 v[142:143], v[136:137], v[136:137], v[142:143]
	v_lshlrev_b32_e32 v130, 16, v110
	v_and_b32_e32 v131, 0xffff0000, v110
	v_lshlrev_b32_e32 v132, 16, v111
	v_and_b32_e32 v133, 0xffff0000, v111
	v_pk_fma_f32 v[94:95], v[130:131], v[130:131], v[94:95]
	v_pk_fma_f32 v[138:139], v[132:133], v[132:133], v[138:139]
	v_lshlrev_b32_e32 v134, 16, v126
	v_and_b32_e32 v135, 0xffff0000, v126
	v_lshlrev_b32_e32 v136, 16, v127
	v_and_b32_e32 v137, 0xffff0000, v127
	v_pk_fma_f32 v[140:141], v[134:135], v[134:135], v[140:141]
	v_pk_fma_f32 v[142:143], v[136:137], v[136:137], v[142:143]
	v_lshlrev_b32_e32 v130, 16, v112
	v_and_b32_e32 v131, 0xffff0000, v112
; __device__ __forceinline__ unsigned cvt_pk_bf16(float lo, float hi) { cvt_f32x2_t v = {lo, hi}; cvt_bf16x2_t b = __builtin_convertvector(v, cvt_bf16x2_t); return __builtin_bit_cast(unsigned, b); }
; __device__ __forceinline__ void rowpass_res(const Frame& F, const Params& p, const float* gpost, const float* gnext, bool first, bool last) {
;     ...
; #pragma unroll
;         for (int u = 0; u < 2; ++u)
; #pragma unroll
;             for (int j = 0; j < 8; ++j) ss[u] += (v[u][j].x * v[u][j].x + v[u][j].y * v[u][j].y) + (v[u][j].z * v[u][j].z + v[u][j].w * v[u][j].w);
;         float rs[2];
; #pragma unroll
;         for (int o = 1; o < 64; o <<= 1) { ss[0] += __shfl_xor(ss[0], o); ss[1] += __shfl_xor(ss[1], o); }
;         rs[0] = rsqrtf(ss[0] * (1.f / D) + EPS); rs[1] = rsqrtf(ss[1] * (1.f / D) + EPS);
;         float ss2[2] = {0.f, 0.f};
; #pragma unroll
;         for (int u = 0; u < 2; ++u) { const int r = r0 + u; bf16* hb = HB + (size_t)r * D;
; #pragma unroll
;             for (int j = 0; j < 8; ++j) { const f32x4 g = *(const f32x4*)(gpost + 4 * F.lane + 256 * j);
;                 v[u][j] = hv[u][j] + v[u][j] * rs[u] * g;
;                 if (last) { if (r < MF) *(f32x4*)(p.out + (size_t)r * D + 4 * F.lane + 256 * j) = v[u][j]; }
;                 else { u32x2 w; w.x = cvt_pk_bf16(v[u][j].x, v[u][j].y); w.y = cvt_pk_bf16(v[u][j].z, v[u][j].w); *(u32x2*)(hb + 4 * F.lane + 256 * j) = w; }
;                 ss2[u] += (v[u][j].x * v[u][j].x + v[u][j].y * v[u][j].y) + (v[u][j].z * v[u][j].z + v[u][j].w * v[u][j].w); } }
	v_lshlrev_b32_e32 v132, 16, v113
	v_and_b32_e32 v133, 0xffff0000, v113
	v_pk_fma_f32 v[94:95], v[130:131], v[130:131], v[94:95]
	v_pk_fma_f32 v[138:139], v[132:133], v[132:133], v[138:139]
	v_lshlrev_b32_e32 v134, 16, v128
	v_and_b32_e32 v135, 0xffff0000, v128
	v_lshlrev_b32_e32 v136, 16, v129
	v_and_b32_e32 v137, 0xffff0000, v129
	v_pk_fma_f32 v[140:141], v[134:135], v[134:135], v[140:141]
	v_pk_fma_f32 v[142:143], v[136:137], v[136:137], v[142:143]
	v_pk_add_f32 v[94:95], v[94:95], v[138:139]
	v_pk_add_f32 v[140:141], v[140:141], v[142:143]
	v_add_f32_e32 v144, v94, v95
	v_add_f32_e32 v146, v140, v141
	v_mov_b32_e32 v148, 0x358637bd
	s_nop 1
	v_add_f32_dpp v144, v144, v144 row_ror:8 row_mask:0xf bank_mask:0xf
	v_add_f32_dpp v146, v146, v146 row_ror:8 row_mask:0xf bank_mask:0xf
	s_nop 1
	v_add_f32_dpp v144, v144, v144 row_ror:4 row_mask:0xf bank_mask:0xf
	v_add_f32_dpp v146, v146, v146 row_ror:4 row_mask:0xf bank_mask:0xf
	s_nop 1
	v_add_f32_dpp v144, v144, v144 row_ror:2 row_mask:0xf bank_mask:0xf
	v_add_f32_dpp v146, v146, v146 row_ror:2 row_mask:0xf bank_mask:0xf
	s_nop 1
	v_add_f32_dpp v144, v144, v144 row_ror:1 row_mask:0xf bank_mask:0xf
	v_add_f32_dpp v146, v146, v146 row_ror:1 row_mask:0xf bank_mask:0xf
	s_nop 1
	v_readlane_b32 s0, v144, 0
	v_readlane_b32 s1, v144, 16
	v_readlane_b32 s6, v144, 32
	v_readlane_b32 s7, v144, 48
	v_readlane_b32 s8, v146, 0
	v_readlane_b32 s9, v146, 16
	v_readlane_b32 s11, v146, 32
	v_readlane_b32 s12, v146, 48
	s_nop 1
	v_mov_b32_e32 v144, s0
	v_mov_b32_e32 v146, s8
	v_add_f32_e32 v144, s1, v144
	v_add_f32_e32 v146, s9, v146
	v_add_f32_e32 v144, s6, v144
	v_add_f32_e32 v146, s11, v146
	v_add_f32_e32 v144, s7, v144
	v_add_f32_e32 v146, s12, v146
	v_fmamk_f32 v144, v144, 0x3a000000, v148
	v_fmamk_f32 v146, v146, 0x3a000000, v148
	v_rsq_f32_e32 v144, v144
	v_rsq_f32_e32 v146, v146
	s_nop 0
	s_waitcnt vmcnt(0)
	s_cmp_lg_u64 s[92:93], 0
	s_cbranch_scc0 .Lrp6_noexp
	v_lshlrev_b32_e32 v0, 16, v2
	v_and_b32_e32 v1, 0xffff0000, v2
	v_lshlrev_b32_e32 v2, 16, v3
	v_and_b32_e32 v3, 0xffff0000, v3
	v_lshlrev_b32_e32 v4, 16, v6
	v_and_b32_e32 v5, 0xffff0000, v6
	v_lshlrev_b32_e32 v6, 16, v7
	v_and_b32_e32 v7, 0xffff0000, v7
	v_lshlrev_b32_e32 v8, 16, v10
	v_and_b32_e32 v9, 0xffff0000, v10
	v_lshlrev_b32_e32 v10, 16, v11
	v_and_b32_e32 v11, 0xffff0000, v11
	v_lshlrev_b32_e32 v12, 16, v14
	v_and_b32_e32 v13, 0xffff0000, v14
	v_lshlrev_b32_e32 v14, 16, v15
	v_and_b32_e32 v15, 0xffff0000, v15
	v_lshlrev_b32_e32 v16, 16, v18
	v_and_b32_e32 v17, 0xffff0000, v18
	v_lshlrev_b32_e32 v18, 16, v19
	v_and_b32_e32 v19, 0xffff0000, v19
	v_lshlrev_b32_e32 v20, 16, v22
	v_and_b32_e32 v21, 0xffff0000, v22
	v_lshlrev_b32_e32 v22, 16, v23
	v_and_b32_e32 v23, 0xffff0000, v23
	v_lshlrev_b32_e32 v24, 16, v26
	v_and_b32_e32 v25, 0xffff0000, v26
	v_lshlrev_b32_e32 v26, 16, v27
	v_and_b32_e32 v27, 0xffff0000, v27
	v_lshlrev_b32_e32 v28, 16, v30
	v_and_b32_e32 v29, 0xffff0000, v30
	v_lshlrev_b32_e32 v30, 16, v31
	v_and_b32_e32 v31, 0xffff0000, v31
	v_lshlrev_b32_e32 v32, 16, v34
	v_and_b32_e32 v33, 0xffff0000, v34
	v_lshlrev_b32_e32 v34, 16, v35
	v_and_b32_e32 v35, 0xffff0000, v35
	v_lshlrev_b32_e32 v36, 16, v38
	v_and_b32_e32 v37, 0xffff0000, v38
	v_lshlrev_b32_e32 v38, 16, v39
	v_and_b32_e32 v39, 0xffff0000, v39
	v_lshlrev_b32_e32 v40, 16, v42
	v_and_b32_e32 v41, 0xffff0000, v42
	v_lshlrev_b32_e32 v42, 16, v43
	v_and_b32_e32 v43, 0xffff0000, v43
	v_lshlrev_b32_e32 v44, 16, v46
	v_and_b32_e32 v45, 0xffff0000, v46
	v_lshlrev_b32_e32 v46, 16, v47
	v_and_b32_e32 v47, 0xffff0000, v47
	v_lshlrev_b32_e32 v48, 16, v50
	v_and_b32_e32 v49, 0xffff0000, v50
	v_lshlrev_b32_e32 v50, 16, v51
	v_and_b32_e32 v51, 0xffff0000, v51
	v_lshlrev_b32_e32 v52, 16, v54
	v_and_b32_e32 v53, 0xffff0000, v54
	v_lshlrev_b32_e32 v54, 16, v55
	v_and_b32_e32 v55, 0xffff0000, v55
	v_lshlrev_b32_e32 v56, 16, v58
	v_and_b32_e32 v57, 0xffff0000, v58
	v_lshlrev_b32_e32 v58, 16, v59
	v_and_b32_e32 v59, 0xffff0000, v59
	v_lshlrev_b32_e32 v60, 16, v62
	v_and_b32_e32 v61, 0xffff0000, v62
	v_lshlrev_b32_e32 v62, 16, v63
	v_and_b32_e32 v63, 0xffff0000, v63
.Lrp6_noexp:
	v_lshlrev_b32_e32 v130, 16, v98
	v_and_b32_e32 v131, 0xffff0000, v98
	v_lshlrev_b32_e32 v132, 16, v99
	v_and_b32_e32 v133, 0xffff0000, v99
	v_pk_mul_f32 v[130:131], v[144:145], v[130:131] op_sel_hi:[0,1]
	v_pk_mul_f32 v[132:133], v[144:145], v[132:133] op_sel_hi:[0,1]
	v_pk_fma_f32 v[0:1], v[130:131], v[204:205], v[0:1]
	v_pk_fma_f32 v[2:3], v[132:133], v[206:207], v[2:3]
	v_pk_mul_f32 v[94:95], v[0:1], v[0:1]
	v_pk_mul_f32 v[138:139], v[2:3], v[2:3]
	v_cvt_pk_bf16_f32 v130, v0, v1
	v_cvt_pk_bf16_f32 v131, v2, v3
	global_store_dwordx2 v[88:89], v[130:131], off offset:-3584
	v_lshlrev_b32_e32 v134, 16, v114
	v_and_b32_e32 v135, 0xffff0000, v114
	v_lshlrev_b32_e32 v136, 16, v115
	v_and_b32_e32 v137, 0xffff0000, v115
	v_pk_mul_f32 v[134:135], v[146:147], v[134:135] op_sel_hi:[0,1]
	v_pk_mul_f32 v[136:137], v[146:147], v[136:137] op_sel_hi:[0,1]
	v_pk_fma_f32 v[32:33], v[134:135], v[204:205], v[32:33]
	v_pk_fma_f32 v[34:35], v[136:137], v[206:207], v[34:35]
	v_pk_mul_f32 v[140:141], v[32:33], v[32:33]
	v_pk_mul_f32 v[142:143], v[34:35], v[34:35]
	v_cvt_pk_bf16_f32 v134, v32, v33
	v_cvt_pk_bf16_f32 v135, v34, v35
	global_store_dwordx2 v[86:87], v[134:135], off offset:-3584
	v_lshlrev_b32_e32 v130, 16, v100
	v_and_b32_e32 v131, 0xffff0000, v100
	v_lshlrev_b32_e32 v132, 16, v101
	v_and_b32_e32 v133, 0xffff0000, v101
	v_pk_mul_f32 v[130:131], v[144:145], v[130:131] op_sel_hi:[0,1]
	v_pk_mul_f32 v[132:133], v[144:145], v[132:133] op_sel_hi:[0,1]
	v_pk_fma_f32 v[4:5], v[130:131], v[208:209], v[4:5]
; __device__ __forceinline__ unsigned cvt_pk_bf16(float lo, float hi) { cvt_f32x2_t v = {lo, hi}; cvt_bf16x2_t b = __builtin_convertvector(v, cvt_bf16x2_t); return __builtin_bit_cast(unsigned, b); }
; __device__ __forceinline__ void rowpass_res(const Frame& F, const Params& p, const float* gpost, const float* gnext, bool first, bool last) {
;     ...
;         for (int u = 0; u < 2; ++u) { const int r = r0 + u; bf16* hb = HB + (size_t)r * D;
; #pragma unroll
;             for (int j = 0; j < 8; ++j) { const f32x4 g = *(const f32x4*)(gpost + 4 * F.lane + 256 * j);
;                 v[u][j] = hv[u][j] + v[u][j] * rs[u] * g;
;                 if (last) { if (r < MF) *(f32x4*)(p.out + (size_t)r * D + 4 * F.lane + 256 * j) = v[u][j]; }
;                 else { u32x2 w; w.x = cvt_pk_bf16(v[u][j].x, v[u][j].y); w.y = cvt_pk_bf16(v[u][j].z, v[u][j].w); *(u32x2*)(hb + 4 * F.lane + 256 * j) = w; }
;                 ss2[u] += (v[u][j].x * v[u][j].x + v[u][j].y * v[u][j].y) + (v[u][j].z * v[u][j].z + v[u][j].w * v[u][j].w); } }
	v_pk_fma_f32 v[6:7], v[132:133], v[210:211], v[6:7]
	v_pk_fma_f32 v[94:95], v[4:5], v[4:5], v[94:95]
	v_pk_fma_f32 v[138:139], v[6:7], v[6:7], v[138:139]
	v_cvt_pk_bf16_f32 v130, v4, v5
	v_cvt_pk_bf16_f32 v131, v6, v7
	global_store_dwordx2 v[88:89], v[130:131], off offset:-3072
	v_lshlrev_b32_e32 v134, 16, v116
	v_and_b32_e32 v135, 0xffff0000, v116
	v_lshlrev_b32_e32 v136, 16, v117
	v_and_b32_e32 v137, 0xffff0000, v117
	v_pk_mul_f32 v[134:135], v[146:147], v[134:135] op_sel_hi:[0,1]
	v_pk_mul_f32 v[136:137], v[146:147], v[136:137] op_sel_hi:[0,1]
	v_pk_fma_f32 v[36:37], v[134:135], v[208:209], v[36:37]
	v_pk_fma_f32 v[38:39], v[136:137], v[210:211], v[38:39]
	v_pk_fma_f32 v[140:141], v[36:37], v[36:37], v[140:141]
	v_pk_fma_f32 v[142:143], v[38:39], v[38:39], v[142:143]
	v_cvt_pk_bf16_f32 v134, v36, v37
	v_cvt_pk_bf16_f32 v135, v38, v39
	global_store_dwordx2 v[86:87], v[134:135], off offset:-3072
	v_lshlrev_b32_e32 v130, 16, v102
	v_and_b32_e32 v131, 0xffff0000, v102
	v_lshlrev_b32_e32 v132, 16, v103
	v_and_b32_e32 v133, 0xffff0000, v103
	v_pk_mul_f32 v[130:131], v[144:145], v[130:131] op_sel_hi:[0,1]
	v_pk_mul_f32 v[132:133], v[144:145], v[132:133] op_sel_hi:[0,1]
	v_pk_fma_f32 v[8:9], v[130:131], v[212:213], v[8:9]
	v_pk_fma_f32 v[10:11], v[132:133], v[214:215], v[10:11]
	v_pk_fma_f32 v[94:95], v[8:9], v[8:9], v[94:95]
	v_pk_fma_f32 v[138:139], v[10:11], v[10:11], v[138:139]
	v_cvt_pk_bf16_f32 v130, v8, v9
	v_cvt_pk_bf16_f32 v131, v10, v11
	global_store_dwordx2 v[88:89], v[130:131], off offset:-2560
	v_lshlrev_b32_e32 v134, 16, v118
	v_and_b32_e32 v135, 0xffff0000, v118
	v_lshlrev_b32_e32 v136, 16, v119
	v_and_b32_e32 v137, 0xffff0000, v119
	v_pk_mul_f32 v[134:135], v[146:147], v[134:135] op_sel_hi:[0,1]
	v_pk_mul_f32 v[136:137], v[146:147], v[136:137] op_sel_hi:[0,1]
	v_pk_fma_f32 v[40:41], v[134:135], v[212:213], v[40:41]
	v_pk_fma_f32 v[42:43], v[136:137], v[214:215], v[42:43]
	v_pk_fma_f32 v[140:141], v[40:41], v[40:41], v[140:141]
	v_pk_fma_f32 v[142:143], v[42:43], v[42:43], v[142:143]
	v_cvt_pk_bf16_f32 v134, v40, v41
	v_cvt_pk_bf16_f32 v135, v42, v43
	global_store_dwordx2 v[86:87], v[134:135], off offset:-2560
	v_lshlrev_b32_e32 v130, 16, v104
	v_and_b32_e32 v131, 0xffff0000, v104
	v_lshlrev_b32_e32 v132, 16, v105
	v_and_b32_e32 v133, 0xffff0000, v105
	v_pk_mul_f32 v[130:131], v[144:145], v[130:131] op_sel_hi:[0,1]
	v_pk_mul_f32 v[132:133], v[144:145], v[132:133] op_sel_hi:[0,1]
	v_pk_fma_f32 v[12:13], v[130:131], v[216:217], v[12:13]
	v_pk_fma_f32 v[14:15], v[132:133], v[218:219], v[14:15]
	v_pk_fma_f32 v[94:95], v[12:13], v[12:13], v[94:95]
	v_pk_fma_f32 v[138:139], v[14:15], v[14:15], v[138:139]
	v_cvt_pk_bf16_f32 v130, v12, v13
	v_cvt_pk_bf16_f32 v131, v14, v15
	global_store_dwordx2 v[88:89], v[130:131], off offset:-2048
	v_lshlrev_b32_e32 v134, 16, v120
	v_and_b32_e32 v135, 0xffff0000, v120
	v_lshlrev_b32_e32 v136, 16, v121
	v_and_b32_e32 v137, 0xffff0000, v121
	v_pk_mul_f32 v[134:135], v[146:147], v[134:135] op_sel_hi:[0,1]
	v_pk_mul_f32 v[136:137], v[146:147], v[136:137] op_sel_hi:[0,1]
	v_pk_fma_f32 v[44:45], v[134:135], v[216:217], v[44:45]
	v_pk_fma_f32 v[46:47], v[136:137], v[218:219], v[46:47]
	v_pk_fma_f32 v[140:141], v[44:45], v[44:45], v[140:141]
	v_pk_fma_f32 v[142:143], v[46:47], v[46:47], v[142:143]
	v_cvt_pk_bf16_f32 v134, v44, v45
	v_cvt_pk_bf16_f32 v135, v46, v47
	global_store_dwordx2 v[86:87], v[134:135], off offset:-2048
	v_lshlrev_b32_e32 v130, 16, v106
	v_and_b32_e32 v131, 0xffff0000, v106
	v_lshlrev_b32_e32 v132, 16, v107
	v_and_b32_e32 v133, 0xffff0000, v107
	v_pk_mul_f32 v[130:131], v[144:145], v[130:131] op_sel_hi:[0,1]
	v_pk_mul_f32 v[132:133], v[144:145], v[132:133] op_sel_hi:[0,1]
	v_pk_fma_f32 v[16:17], v[130:131], v[220:221], v[16:17]
	v_pk_fma_f32 v[18:19], v[132:133], v[222:223], v[18:19]
	v_pk_fma_f32 v[94:95], v[16:17], v[16:17], v[94:95]
	v_pk_fma_f32 v[138:139], v[18:19], v[18:19], v[138:139]
	v_cvt_pk_bf16_f32 v130, v16, v17
	v_cvt_pk_bf16_f32 v131, v18, v19
	global_store_dwordx2 v[88:89], v[130:131], off offset:-1536
	v_lshlrev_b32_e32 v134, 16, v122
	v_and_b32_e32 v135, 0xffff0000, v122
	v_lshlrev_b32_e32 v136, 16, v123
	v_and_b32_e32 v137, 0xffff0000, v123
	v_pk_mul_f32 v[134:135], v[146:147], v[134:135] op_sel_hi:[0,1]
	v_pk_mul_f32 v[136:137], v[146:147], v[136:137] op_sel_hi:[0,1]
	v_pk_fma_f32 v[48:49], v[134:135], v[220:221], v[48:49]
	v_pk_fma_f32 v[50:51], v[136:137], v[222:223], v[50:51]
	v_pk_fma_f32 v[140:141], v[48:49], v[48:49], v[140:141]
	v_pk_fma_f32 v[142:143], v[50:51], v[50:51], v[142:143]
	v_cvt_pk_bf16_f32 v134, v48, v49
	v_cvt_pk_bf16_f32 v135, v50, v51
	global_store_dwordx2 v[86:87], v[134:135], off offset:-1536
	v_lshlrev_b32_e32 v130, 16, v108
	v_and_b32_e32 v131, 0xffff0000, v108
	v_lshlrev_b32_e32 v132, 16, v109
	v_and_b32_e32 v133, 0xffff0000, v109
	v_pk_mul_f32 v[130:131], v[144:145], v[130:131] op_sel_hi:[0,1]
	v_pk_mul_f32 v[132:133], v[144:145], v[132:133] op_sel_hi:[0,1]
	v_pk_fma_f32 v[20:21], v[130:131], v[224:225], v[20:21]
	v_pk_fma_f32 v[22:23], v[132:133], v[226:227], v[22:23]
	v_pk_fma_f32 v[94:95], v[20:21], v[20:21], v[94:95]
	v_pk_fma_f32 v[138:139], v[22:23], v[22:23], v[138:139]
	v_cvt_pk_bf16_f32 v130, v20, v21
	v_cvt_pk_bf16_f32 v131, v22, v23
	global_store_dwordx2 v[88:89], v[130:131], off offset:-1024
	v_lshlrev_b32_e32 v134, 16, v124
	v_and_b32_e32 v135, 0xffff0000, v124
	v_lshlrev_b32_e32 v136, 16, v125
	v_and_b32_e32 v137, 0xffff0000, v125
	v_pk_mul_f32 v[134:135], v[146:147], v[134:135] op_sel_hi:[0,1]
	v_pk_mul_f32 v[136:137], v[146:147], v[136:137] op_sel_hi:[0,1]
	v_pk_fma_f32 v[52:53], v[134:135], v[224:225], v[52:53]
; __device__ __forceinline__ unsigned cvt_pk_bf16(float lo, float hi) { cvt_f32x2_t v = {lo, hi}; cvt_bf16x2_t b = __builtin_convertvector(v, cvt_bf16x2_t); return __builtin_bit_cast(unsigned, b); }
; __device__ __forceinline__ void rowpass_res(const Frame& F, const Params& p, const float* gpost, const float* gnext, bool first, bool last) {
;     ...
;         for (int u = 0; u < 2; ++u) { const int r = r0 + u; bf16* hb = HB + (size_t)r * D;
; #pragma unroll
;             for (int j = 0; j < 8; ++j) { const f32x4 g = *(const f32x4*)(gpost + 4 * F.lane + 256 * j);
;                 v[u][j] = hv[u][j] + v[u][j] * rs[u] * g;
;                 if (last) { if (r < MF) *(f32x4*)(p.out + (size_t)r * D + 4 * F.lane + 256 * j) = v[u][j]; }
;                 else { u32x2 w; w.x = cvt_pk_bf16(v[u][j].x, v[u][j].y); w.y = cvt_pk_bf16(v[u][j].z, v[u][j].w); *(u32x2*)(hb + 4 * F.lane + 256 * j) = w; }
;                 ss2[u] += (v[u][j].x * v[u][j].x + v[u][j].y * v[u][j].y) + (v[u][j].z * v[u][j].z + v[u][j].w * v[u][j].w); } }
;         if (gnext) {
; #pragma unroll
;             for (int o = 1; o < 64; o <<= 1) { ss2[0] += __shfl_xor(ss2[0], o); ss2[1] += __shfl_xor(ss2[1], o); }
; #pragma unroll
;             for (int u = 0; u < 2; ++u) { const float rs2 = rsqrtf(ss2[u] * (1.f / D) + EPS);
; #pragma unroll
;                 for (int j = 0; j < 8; ++j) { const f32x4 g = *(const f32x4*)(gnext + 4 * F.lane + 256 * j);
;                     u32x2 w; w.x = cvt_pk_bf16(v[u][j].x * rs2 * g.x, v[u][j].y * rs2 * g.y); w.y = cvt_pk_bf16(v[u][j].z * rs2 * g.z, v[u][j].w * rs2 * g.w);
;                     *(u32x2*)(A + (size_t)(r0 + u) * D + 4 * F.lane + 256 * j) = w; } }
	v_pk_fma_f32 v[54:55], v[136:137], v[226:227], v[54:55]
	v_pk_fma_f32 v[140:141], v[52:53], v[52:53], v[140:141]
	v_pk_fma_f32 v[142:143], v[54:55], v[54:55], v[142:143]
	v_cvt_pk_bf16_f32 v134, v52, v53
	v_cvt_pk_bf16_f32 v135, v54, v55
	global_store_dwordx2 v[86:87], v[134:135], off offset:-1024
	v_lshlrev_b32_e32 v130, 16, v110
	v_and_b32_e32 v131, 0xffff0000, v110
	v_lshlrev_b32_e32 v132, 16, v111
	v_and_b32_e32 v133, 0xffff0000, v111
	v_pk_mul_f32 v[130:131], v[144:145], v[130:131] op_sel_hi:[0,1]
	v_pk_mul_f32 v[132:133], v[144:145], v[132:133] op_sel_hi:[0,1]
	v_pk_fma_f32 v[24:25], v[130:131], v[228:229], v[24:25]
	v_pk_fma_f32 v[26:27], v[132:133], v[230:231], v[26:27]
	v_pk_fma_f32 v[94:95], v[24:25], v[24:25], v[94:95]
	v_pk_fma_f32 v[138:139], v[26:27], v[26:27], v[138:139]
	v_cvt_pk_bf16_f32 v130, v24, v25
	v_cvt_pk_bf16_f32 v131, v26, v27
	global_store_dwordx2 v[88:89], v[130:131], off offset:-512
	v_lshlrev_b32_e32 v134, 16, v126
	v_and_b32_e32 v135, 0xffff0000, v126
	v_lshlrev_b32_e32 v136, 16, v127
	v_and_b32_e32 v137, 0xffff0000, v127
	v_pk_mul_f32 v[134:135], v[146:147], v[134:135] op_sel_hi:[0,1]
	v_pk_mul_f32 v[136:137], v[146:147], v[136:137] op_sel_hi:[0,1]
	v_pk_fma_f32 v[56:57], v[134:135], v[228:229], v[56:57]
	v_pk_fma_f32 v[58:59], v[136:137], v[230:231], v[58:59]
	v_pk_fma_f32 v[140:141], v[56:57], v[56:57], v[140:141]
	v_pk_fma_f32 v[142:143], v[58:59], v[58:59], v[142:143]
	v_cvt_pk_bf16_f32 v134, v56, v57
	v_cvt_pk_bf16_f32 v135, v58, v59
	global_store_dwordx2 v[86:87], v[134:135], off offset:-512
	v_lshlrev_b32_e32 v130, 16, v112
	v_and_b32_e32 v131, 0xffff0000, v112
	v_lshlrev_b32_e32 v132, 16, v113
	v_and_b32_e32 v133, 0xffff0000, v113
	v_pk_mul_f32 v[130:131], v[144:145], v[130:131] op_sel_hi:[0,1]
	v_pk_mul_f32 v[132:133], v[144:145], v[132:133] op_sel_hi:[0,1]
	v_pk_fma_f32 v[28:29], v[130:131], v[232:233], v[28:29]
	v_pk_fma_f32 v[30:31], v[132:133], v[234:235], v[30:31]
	v_pk_fma_f32 v[94:95], v[28:29], v[28:29], v[94:95]
	v_pk_fma_f32 v[138:139], v[30:31], v[30:31], v[138:139]
	v_cvt_pk_bf16_f32 v130, v28, v29
	v_cvt_pk_bf16_f32 v131, v30, v31
	global_store_dwordx2 v[88:89], v[130:131], off
	v_lshlrev_b32_e32 v134, 16, v128
	v_and_b32_e32 v135, 0xffff0000, v128
	v_lshlrev_b32_e32 v136, 16, v129
	v_and_b32_e32 v137, 0xffff0000, v129
	v_pk_mul_f32 v[134:135], v[146:147], v[134:135] op_sel_hi:[0,1]
	v_pk_mul_f32 v[136:137], v[146:147], v[136:137] op_sel_hi:[0,1]
	v_pk_fma_f32 v[60:61], v[134:135], v[232:233], v[60:61]
	v_pk_fma_f32 v[62:63], v[136:137], v[234:235], v[62:63]
	v_pk_fma_f32 v[140:141], v[60:61], v[60:61], v[140:141]
	v_pk_fma_f32 v[142:143], v[62:63], v[62:63], v[142:143]
	v_cvt_pk_bf16_f32 v134, v60, v61
	v_cvt_pk_bf16_f32 v135, v62, v63
	global_store_dwordx2 v[86:87], v[134:135], off
	s_cmp_lg_u64 s[36:37], 0
	s_cbranch_scc0 .LBB0_851
	v_pk_add_f32 v[94:95], v[94:95], v[138:139]
	v_pk_add_f32 v[140:141], v[140:141], v[142:143]
	v_add_f32_e32 v144, v94, v95
	v_add_f32_e32 v146, v140, v141
	v_mov_b32_e32 v148, 0x358637bd
	s_nop 1
	v_add_f32_dpp v144, v144, v144 row_ror:8 row_mask:0xf bank_mask:0xf
	v_add_f32_dpp v146, v146, v146 row_ror:8 row_mask:0xf bank_mask:0xf
	s_nop 1
	v_add_f32_dpp v144, v144, v144 row_ror:4 row_mask:0xf bank_mask:0xf
	v_add_f32_dpp v146, v146, v146 row_ror:4 row_mask:0xf bank_mask:0xf
	s_nop 1
	v_add_f32_dpp v144, v144, v144 row_ror:2 row_mask:0xf bank_mask:0xf
	v_add_f32_dpp v146, v146, v146 row_ror:2 row_mask:0xf bank_mask:0xf
	s_nop 1
	v_add_f32_dpp v144, v144, v144 row_ror:1 row_mask:0xf bank_mask:0xf
	v_add_f32_dpp v146, v146, v146 row_ror:1 row_mask:0xf bank_mask:0xf
	s_nop 1
	v_readlane_b32 s0, v144, 0
	v_readlane_b32 s1, v144, 16
	v_readlane_b32 s6, v144, 32
	v_readlane_b32 s7, v144, 48
	v_readlane_b32 s8, v146, 0
	v_readlane_b32 s9, v146, 16
	v_readlane_b32 s11, v146, 32
	v_readlane_b32 s12, v146, 48
	s_nop 1
	v_mov_b32_e32 v144, s0
	v_mov_b32_e32 v146, s8
	v_add_f32_e32 v144, s1, v144
	v_add_f32_e32 v146, s9, v146
	v_add_f32_e32 v144, s6, v144
	v_add_f32_e32 v146, s11, v146
	v_add_f32_e32 v144, s7, v144
	v_add_f32_e32 v146, s12, v146
	v_fmamk_f32 v144, v144, 0x3a000000, v148
	v_fmamk_f32 v146, v146, 0x3a000000, v148
	v_rsq_f32_e32 v144, v144
	v_rsq_f32_e32 v146, v146
	s_nop 0
	v_add_co_u32_e32 v90, vcc, 0xd1480000, v88
	s_nop 1
	v_addc_co_u32_e32 v91, vcc, -1, v89, vcc
	v_add_co_u32_e32 v92, vcc, 0xd1480000, v86
	s_nop 1
	v_addc_co_u32_e32 v93, vcc, -1, v87, vcc
	v_pk_mul_f32 v[130:131], v[144:145], v[0:1] op_sel_hi:[0,1]
	v_pk_mul_f32 v[132:133], v[144:145], v[2:3] op_sel_hi:[0,1]
	v_pk_mul_f32 v[130:131], v[130:131], v[236:237]
	v_pk_mul_f32 v[132:133], v[132:133], v[238:239]
	v_cvt_pk_bf16_f32 v130, v130, v131
	v_cvt_pk_bf16_f32 v131, v132, v133
	global_store_dwordx2 v[90:91], v[130:131], off offset:-3584
	v_pk_mul_f32 v[134:135], v[146:147], v[32:33] op_sel_hi:[0,1]
	v_pk_mul_f32 v[136:137], v[146:147], v[34:35] op_sel_hi:[0,1]
	v_pk_mul_f32 v[134:135], v[134:135], v[236:237]
	v_pk_mul_f32 v[136:137], v[136:137], v[238:239]
	v_cvt_pk_bf16_f32 v134, v134, v135
; __device__ __forceinline__ unsigned cvt_pk_bf16(float lo, float hi) { cvt_f32x2_t v = {lo, hi}; cvt_bf16x2_t b = __builtin_convertvector(v, cvt_bf16x2_t); return __builtin_bit_cast(unsigned, b); }
; __device__ __forceinline__ void rowpass_res(const Frame& F, const Params& p, const float* gpost, const float* gnext, bool first, bool last) {
;     ...
;             for (int u = 0; u < 2; ++u) { const float rs2 = rsqrtf(ss2[u] * (1.f / D) + EPS);
; #pragma unroll
;                 for (int j = 0; j < 8; ++j) { const f32x4 g = *(const f32x4*)(gnext + 4 * F.lane + 256 * j);
;                     u32x2 w; w.x = cvt_pk_bf16(v[u][j].x * rs2 * g.x, v[u][j].y * rs2 * g.y); w.y = cvt_pk_bf16(v[u][j].z * rs2 * g.z, v[u][j].w * rs2 * g.w);
;                     *(u32x2*)(A + (size_t)(r0 + u) * D + 4 * F.lane + 256 * j) = w; } }
	v_cvt_pk_bf16_f32 v135, v136, v137
	global_store_dwordx2 v[92:93], v[134:135], off offset:-3584
	v_pk_mul_f32 v[130:131], v[144:145], v[4:5] op_sel_hi:[0,1]
	v_pk_mul_f32 v[132:133], v[144:145], v[6:7] op_sel_hi:[0,1]
	v_pk_mul_f32 v[130:131], v[130:131], v[240:241]
	v_pk_mul_f32 v[132:133], v[132:133], v[242:243]
	v_cvt_pk_bf16_f32 v130, v130, v131
	v_cvt_pk_bf16_f32 v131, v132, v133
	global_store_dwordx2 v[90:91], v[130:131], off offset:-3072
	v_pk_mul_f32 v[134:135], v[146:147], v[36:37] op_sel_hi:[0,1]
	v_pk_mul_f32 v[136:137], v[146:147], v[38:39] op_sel_hi:[0,1]
	v_pk_mul_f32 v[134:135], v[134:135], v[240:241]
	v_pk_mul_f32 v[136:137], v[136:137], v[242:243]
	v_cvt_pk_bf16_f32 v134, v134, v135
	v_cvt_pk_bf16_f32 v135, v136, v137
	global_store_dwordx2 v[92:93], v[134:135], off offset:-3072
	v_pk_mul_f32 v[130:131], v[144:145], v[8:9] op_sel_hi:[0,1]
	v_pk_mul_f32 v[132:133], v[144:145], v[10:11] op_sel_hi:[0,1]
	v_pk_mul_f32 v[130:131], v[130:131], v[244:245]
	v_pk_mul_f32 v[132:133], v[132:133], v[246:247]
	v_cvt_pk_bf16_f32 v130, v130, v131
	v_cvt_pk_bf16_f32 v131, v132, v133
	global_store_dwordx2 v[90:91], v[130:131], off offset:-2560
	v_pk_mul_f32 v[134:135], v[146:147], v[40:41] op_sel_hi:[0,1]
	v_pk_mul_f32 v[136:137], v[146:147], v[42:43] op_sel_hi:[0,1]
	v_pk_mul_f32 v[134:135], v[134:135], v[244:245]
	v_pk_mul_f32 v[136:137], v[136:137], v[246:247]
	v_cvt_pk_bf16_f32 v134, v134, v135
	v_cvt_pk_bf16_f32 v135, v136, v137
	global_store_dwordx2 v[92:93], v[134:135], off offset:-2560
	v_pk_mul_f32 v[130:131], v[144:145], v[12:13] op_sel_hi:[0,1]
	v_pk_mul_f32 v[132:133], v[144:145], v[14:15] op_sel_hi:[0,1]
	v_pk_mul_f32 v[130:131], v[130:131], v[248:249]
	v_pk_mul_f32 v[132:133], v[132:133], v[250:251]
	v_cvt_pk_bf16_f32 v130, v130, v131
	v_cvt_pk_bf16_f32 v131, v132, v133
	global_store_dwordx2 v[90:91], v[130:131], off offset:-2048
	v_pk_mul_f32 v[134:135], v[146:147], v[44:45] op_sel_hi:[0,1]
	v_pk_mul_f32 v[136:137], v[146:147], v[46:47] op_sel_hi:[0,1]
	v_pk_mul_f32 v[134:135], v[134:135], v[248:249]
	v_pk_mul_f32 v[136:137], v[136:137], v[250:251]
	v_cvt_pk_bf16_f32 v134, v134, v135
	v_cvt_pk_bf16_f32 v135, v136, v137
	global_store_dwordx2 v[92:93], v[134:135], off offset:-2048
	v_pk_mul_f32 v[130:131], v[144:145], v[16:17] op_sel_hi:[0,1]
	v_pk_mul_f32 v[132:133], v[144:145], v[18:19] op_sel_hi:[0,1]
	v_pk_mul_f32 v[130:131], v[130:131], v[186:187]
	v_pk_mul_f32 v[132:133], v[132:133], v[188:189]
	v_cvt_pk_bf16_f32 v130, v130, v131
	v_cvt_pk_bf16_f32 v131, v132, v133
	global_store_dwordx2 v[90:91], v[130:131], off offset:-1536
	v_pk_mul_f32 v[134:135], v[146:147], v[48:49] op_sel_hi:[0,1]
	v_pk_mul_f32 v[136:137], v[146:147], v[50:51] op_sel_hi:[0,1]
	v_pk_mul_f32 v[134:135], v[134:135], v[186:187]
	v_pk_mul_f32 v[136:137], v[136:137], v[188:189]
	v_cvt_pk_bf16_f32 v134, v134, v135
	v_cvt_pk_bf16_f32 v135, v136, v137
	global_store_dwordx2 v[92:93], v[134:135], off offset:-1536
	v_pk_mul_f32 v[130:131], v[144:145], v[20:21] op_sel_hi:[0,1]
	v_pk_mul_f32 v[132:133], v[144:145], v[22:23] op_sel_hi:[0,1]
	v_pk_mul_f32 v[130:131], v[130:131], v[190:191]
	v_pk_mul_f32 v[132:133], v[132:133], v[192:193]
	v_cvt_pk_bf16_f32 v130, v130, v131
	v_cvt_pk_bf16_f32 v131, v132, v133
	global_store_dwordx2 v[90:91], v[130:131], off offset:-1024
	v_pk_mul_f32 v[134:135], v[146:147], v[52:53] op_sel_hi:[0,1]
	v_pk_mul_f32 v[136:137], v[146:147], v[54:55] op_sel_hi:[0,1]
	v_pk_mul_f32 v[134:135], v[134:135], v[190:191]
	v_pk_mul_f32 v[136:137], v[136:137], v[192:193]
	v_cvt_pk_bf16_f32 v134, v134, v135
	v_cvt_pk_bf16_f32 v135, v136, v137
	global_store_dwordx2 v[92:93], v[134:135], off offset:-1024
	v_pk_mul_f32 v[130:131], v[144:145], v[24:25] op_sel_hi:[0,1]
	v_pk_mul_f32 v[132:133], v[144:145], v[26:27] op_sel_hi:[0,1]
	v_pk_mul_f32 v[130:131], v[130:131], v[194:195]
	v_pk_mul_f32 v[132:133], v[132:133], v[196:197]
	v_cvt_pk_bf16_f32 v130, v130, v131
	v_cvt_pk_bf16_f32 v131, v132, v133
	global_store_dwordx2 v[90:91], v[130:131], off offset:-512
	v_pk_mul_f32 v[134:135], v[146:147], v[56:57] op_sel_hi:[0,1]
	v_pk_mul_f32 v[136:137], v[146:147], v[58:59] op_sel_hi:[0,1]
	v_pk_mul_f32 v[134:135], v[134:135], v[194:195]
	v_pk_mul_f32 v[136:137], v[136:137], v[196:197]
	v_cvt_pk_bf16_f32 v134, v134, v135
	v_cvt_pk_bf16_f32 v135, v136, v137
	global_store_dwordx2 v[92:93], v[134:135], off offset:-512
	v_pk_mul_f32 v[130:131], v[144:145], v[28:29] op_sel_hi:[0,1]
	v_pk_mul_f32 v[132:133], v[144:145], v[30:31] op_sel_hi:[0,1]
	v_pk_mul_f32 v[130:131], v[130:131], v[198:199]
	v_pk_mul_f32 v[132:133], v[132:133], v[200:201]
	v_cvt_pk_bf16_f32 v130, v130, v131
	v_cvt_pk_bf16_f32 v131, v132, v133
	global_store_dwordx2 v[90:91], v[130:131], off
	v_pk_mul_f32 v[134:135], v[146:147], v[60:61] op_sel_hi:[0,1]
	v_pk_mul_f32 v[136:137], v[146:147], v[62:63] op_sel_hi:[0,1]
	v_pk_mul_f32 v[134:135], v[134:135], v[198:199]
	v_pk_mul_f32 v[136:137], v[136:137], v[200:201]
	v_cvt_pk_bf16_f32 v134, v134, v135
	v_cvt_pk_bf16_f32 v135, v136, v137
	global_store_dwordx2 v[92:93], v[134:135], off
	s_branch .LBB0_851

; __device__ __forceinline__ float bflo(unsigned w) { return __uint_as_float(w << 16); }
; __device__ __forceinline__ float bfhi(unsigned w) { return __uint_as_float(w & 0xffff0000u); }
; __device__ __forceinline__ void rowpass_res(const Frame& F, const Params& p, const float* gpost, const float* gnext, bool first, bool last) {
;     bf16* A = (bf16*)(p.ws + WS_A); const bf16* Msrc = (const bf16*)(p.ws + WS_M); bf16* HB = (bf16*)(p.ws + WS_HB);
;     for (int r0 = 2 * F.gw; r0 < MREAL; r0 += 2 * F.ngw) {
;         f32x4 v[2][8]; float ss[2] = {0.f, 0.f};
; #pragma unroll
;         for (int u = 0; u < 2; ++u) { const bf16* ms = Msrc + (size_t)(r0 + u) * D;
; #pragma unroll
;             for (int j = 0; j < 8; ++j) { const u32x2 mw = *(const u32x2*)(ms + 4 * F.lane + 256 * j); v[u][j] = (f32x4){bflo(mw.x), bfhi(mw.x), bflo(mw.y), bfhi(mw.y)}; } }
;         f32x4 hv[2][8];
; #pragma unroll
;         for (int u = 0; u < 2; ++u) { const int r = r0 + u; const bf16* hb = HB + (size_t)r * D;
; #pragma unroll
;             for (int j = 0; j < 8; ++j) {
;                 if (first) hv[u][j] = *(const f32x4*)((r < MF ? p.x + (size_t)r * D : p.meta + (size_t)(r - MF) * D) + 4 * F.lane + 256 * j);
;                 else { const u32x2 hw = *(const u32x2*)(hb + 4 * F.lane + 256 * j); hv[u][j] = (f32x4){bflo(hw.x), bfhi(hw.x), bflo(hw.y), bfhi(hw.y)}; } } }
.LBB0_1201:
	s_or_b64 exec, exec, s[0:1]
	v_readlane_b32 s0, v254, 18
	s_waitcnt lgkmcnt(0)
	s_barrier
	v_mbcnt_lo_u32_b32 v0, -1, 0
	v_mbcnt_hi_u32_b32 v0, -1, v0
	s_nop 0
	v_add_u32_e32 v137, s0, v0
	s_nop 0
	v_readfirstlane_b32 s0, v137
	s_ashr_i32 s11, s0, 6
	v_readlane_b32 s0, v254, 19
	s_lshl_b32 s0, s0, 3
	s_add_i32 s10, s0, s11
	v_and_b32_e32 v136, 63, v137
	s_mov_b32 s0, s53
	s_cmpk_gt_i32 s10, 0x2007
	s_cbranch_scc1 .LBB0_1286
	v_and_b32_e32 v0, 64, v202
	v_add_u32_e32 v0, 64, v0
	v_xor_b32_e32 v1, 1, v202
	v_cmp_lt_i32_e32 vcc, v1, v0
	s_and_b64 s[0:1], s[66:67], exec
	v_readlane_b32 s0, v254, 53
	v_cndmask_b32_e32 v1, v202, v1, vcc
	v_lshlrev_b32_e32 v138, 2, v1
	v_xor_b32_e32 v1, 2, v202
	v_cmp_lt_i32_e32 vcc, v1, v0
	s_cselect_b32 s1, s0, 0
	v_readlane_b32 s0, v254, 52
	v_cndmask_b32_e32 v1, v202, v1, vcc
	v_lshlrev_b32_e32 v139, 2, v1
	v_xor_b32_e32 v1, 4, v202
	v_cmp_lt_i32_e32 vcc, v1, v0
	s_cselect_b32 s0, s0, 0
	s_lshl_b64 s[2:3], s[4:5], 2
	v_cndmask_b32_e32 v1, v202, v1, vcc
	v_lshlrev_b32_e32 v140, 2, v1
	v_xor_b32_e32 v1, 8, v202
	v_cmp_lt_i32_e32 vcc, v1, v0
	s_add_u32 s2, s58, s2
	s_addc_u32 s3, s59, s3
	v_cndmask_b32_e32 v1, v202, v1, vcc
	v_lshlrev_b32_e32 v141, 2, v1
	v_xor_b32_e32 v1, 16, v202
	v_cmp_lt_i32_e32 vcc, v1, v0
	s_lshl_b32 s6, s10, 1
	v_lshlrev_b32_e32 v96, 4, v136
	v_cndmask_b32_e32 v1, v202, v1, vcc
	v_lshlrev_b32_e32 v142, 2, v1
	v_xor_b32_e32 v1, 32, v202
	v_lshl_add_u64 v[64:65], s[2:3], 0, v[96:97]
	s_mov_b64 s[2:3], 0x1000
	v_lshl_add_u64 v[74:75], s[0:1], 0, v[96:97]
	s_ashr_i32 s7, s6, 31
	v_cmp_lt_i32_e32 vcc, v1, v0
	v_lshl_add_u64 v[66:67], v[64:65], 0, s[2:3]
	v_lshl_add_u64 v[76:77], v[74:75], 0, s[2:3]
	s_lshl_b64 s[0:1], s[6:7], 12
	v_readlane_b32 s2, v255, 12
	v_cndmask_b32_e32 v0, v202, v1, vcc
	s_add_u32 s0, s2, s0
	v_readlane_b32 s2, v255, 13
	v_lshlrev_b32_e32 v143, 2, v0
	v_lshlrev_b32_e32 v0, 3, v136
	v_mov_b32_e32 v1, v97
	s_addc_u32 s1, s2, s1
	v_lshl_add_u64 v[84:85], s[0:1], 0, v[0:1]
	s_lshl_b64 s[0:1], s[6:7], 13
	v_readlane_b32 s2, v255, 16
	s_add_u32 s0, s2, s0
	v_readlane_b32 s2, v255, 17
	s_mov_b64 s[4:5], 0x1400
	s_mov_b64 s[8:9], 0x1800
	s_mov_b64 s[12:13], 0x1c00
	s_addc_u32 s1, s2, s1
	v_lshl_add_u64 v[68:69], v[64:65], 0, s[4:5]
	v_lshl_add_u64 v[70:71], v[64:65], 0, s[8:9]
	v_lshl_add_u64 v[72:73], v[64:65], 0, s[12:13]
	v_lshl_add_u64 v[78:79], v[74:75], 0, s[4:5]
	v_lshl_add_u64 v[80:81], v[74:75], 0, s[8:9]
	v_lshl_add_u64 v[82:83], v[74:75], 0, s[12:13]
	v_lshl_add_u64 v[86:87], s[0:1], 0, v[96:97]
	s_mov_b32 s12, 0x3a000000
	global_load_dwordx4 v[204:207], v[64:65], off
	global_load_dwordx4 v[208:211], v[64:65], off offset:1024
	global_load_dwordx4 v[212:215], v[64:65], off offset:2048
	global_load_dwordx4 v[216:219], v[64:65], off offset:3072
	global_load_dwordx4 v[220:223], v[66:67], off
	global_load_dwordx4 v[224:227], v[66:67], off offset:1024
	global_load_dwordx4 v[228:231], v[66:67], off offset:2048
	global_load_dwordx4 v[232:235], v[66:67], off offset:3072
	s_cmp_lg_u64 s[66:67], 0
	s_cbranch_scc0 .Lrp9_nogn
	global_load_dwordx4 v[236:239], v[74:75], off
	global_load_dwordx4 v[240:243], v[74:75], off offset:1024
	global_load_dwordx4 v[244:247], v[74:75], off offset:2048
	global_load_dwordx4 v[248:251], v[74:75], off offset:3072
	global_load_dwordx4 v[186:189], v[76:77], off
	global_load_dwordx4 v[190:193], v[76:77], off offset:1024
	global_load_dwordx4 v[194:197], v[76:77], off offset:2048
	global_load_dwordx4 v[198:201], v[76:77], off offset:3072
.Lrp9_nogn:
	s_branch .LBB0_1204
.LBB0_1203:
	v_readlane_b32 s0, v255, 14
	s_add_i32 s6, s6, s26
	v_readlane_b32 s1, v255, 15
	s_cmpk_lt_i32 s6, 0x4010
	v_lshl_add_u64 v[86:87], v[86:87], 0, s[60:61]
	v_lshl_add_u64 v[84:85], v[84:85], 0, s[0:1]
	s_cbranch_scc0 .LBB0_1286
.LBB0_1204:
	v_add_co_u32_e32 v88, vcc, 0xfffff000, v84
	s_nop 1
	v_addc_co_u32_e32 v89, vcc, -1, v85, vcc
	v_add_co_u32_e32 v92, vcc, 0xe1880000, v84
	s_nop 1
	v_addc_co_u32_e32 v93, vcc, -1, v85, vcc
	v_add_co_u32_e32 v90, vcc, 0xe1880000, v88
	s_nop 1
	v_addc_co_u32_e32 v91, vcc, -1, v89, vcc
	global_load_dwordx2 v[98:99], v[90:91], off offset:-3584
	global_load_dwordx2 v[100:101], v[90:91], off offset:-3072
	global_load_dwordx2 v[102:103], v[90:91], off offset:-2560
	global_load_dwordx2 v[104:105], v[90:91], off offset:-2048
	global_load_dwordx2 v[106:107], v[90:91], off offset:-1536
	global_load_dwordx2 v[108:109], v[90:91], off offset:-1024
	global_load_dwordx2 v[110:111], v[90:91], off offset:-512
	global_load_dwordx2 v[112:113], v[90:91], off
	global_load_dwordx2 v[114:115], v[92:93], off offset:-3584
	global_load_dwordx2 v[116:117], v[92:93], off offset:-3072
	global_load_dwordx2 v[118:119], v[92:93], off offset:-2560
	global_load_dwordx2 v[120:121], v[92:93], off offset:-2048
	global_load_dwordx2 v[122:123], v[92:93], off offset:-1536
	global_load_dwordx2 v[124:125], v[92:93], off offset:-1024
	global_load_dwordx2 v[126:127], v[92:93], off offset:-512
	global_load_dwordx2 v[128:129], v[92:93], off
	global_load_dwordx2 v[2:3], v[88:89], off offset:-3584
	global_load_dwordx2 v[6:7], v[88:89], off offset:-3072
	global_load_dwordx2 v[10:11], v[88:89], off offset:-2560
	global_load_dwordx2 v[14:15], v[88:89], off offset:-2048
	global_load_dwordx2 v[18:19], v[88:89], off offset:-1536
	global_load_dwordx2 v[22:23], v[88:89], off offset:-1024
	global_load_dwordx2 v[26:27], v[88:89], off offset:-512
	global_load_dwordx2 v[30:31], v[88:89], off
	global_load_dwordx2 v[34:35], v[84:85], off offset:-3584
	global_load_dwordx2 v[38:39], v[84:85], off offset:-3072
	global_load_dwordx2 v[42:43], v[84:85], off offset:-2560
	global_load_dwordx2 v[46:47], v[84:85], off offset:-2048
	global_load_dwordx2 v[50:51], v[84:85], off offset:-1536
	global_load_dwordx2 v[54:55], v[84:85], off offset:-1024
	global_load_dwordx2 v[58:59], v[84:85], off offset:-512
	global_load_dwordx2 v[62:63], v[84:85], off
	s_waitcnt vmcnt(16)
; __device__ __forceinline__ void rowpass_res(const Frame& F, const Params& p, const float* gpost, const float* gnext, bool first, bool last) {
;     ...
; #pragma unroll
;         for (int u = 0; u < 2; ++u)
; #pragma unroll
;             for (int j = 0; j < 8; ++j) ss[u] += (v[u][j].x * v[u][j].x + v[u][j].y * v[u][j].y) + (v[u][j].z * v[u][j].z + v[u][j].w * v[u][j].w);
;         float rs[2];
; #pragma unroll
;         for (int o = 1; o < 64; o <<= 1) { ss[0] += __shfl_xor(ss[0], o); ss[1] += __shfl_xor(ss[1], o); }
;         rs[0] = rsqrtf(ss[0] * (1.f / D) + EPS); rs[1] = rsqrtf(ss[1] * (1.f / D) + EPS);
	v_lshlrev_b32_e32 v130, 16, v98
	v_and_b32_e32 v131, 0xffff0000, v98
	v_lshlrev_b32_e32 v132, 16, v99
	v_and_b32_e32 v133, 0xffff0000, v99
	v_pk_mul_f32 v[94:95], v[130:131], v[130:131]
	v_pk_mul_f32 v[134:135], v[132:133], v[132:133]
	v_lshlrev_b32_e32 v144, 16, v114
	v_and_b32_e32 v145, 0xffff0000, v114
	v_lshlrev_b32_e32 v146, 16, v115
	v_and_b32_e32 v147, 0xffff0000, v115
	v_pk_mul_f32 v[148:149], v[144:145], v[144:145]
	v_pk_mul_f32 v[150:151], v[146:147], v[146:147]
	v_lshlrev_b32_e32 v130, 16, v100
	v_and_b32_e32 v131, 0xffff0000, v100
	v_lshlrev_b32_e32 v132, 16, v101
	v_and_b32_e32 v133, 0xffff0000, v101
	v_pk_fma_f32 v[94:95], v[130:131], v[130:131], v[94:95]
	v_pk_fma_f32 v[134:135], v[132:133], v[132:133], v[134:135]
	v_lshlrev_b32_e32 v144, 16, v116
	v_and_b32_e32 v145, 0xffff0000, v116
	v_lshlrev_b32_e32 v146, 16, v117
	v_and_b32_e32 v147, 0xffff0000, v117
	v_pk_fma_f32 v[148:149], v[144:145], v[144:145], v[148:149]
	v_pk_fma_f32 v[150:151], v[146:147], v[146:147], v[150:151]
	v_lshlrev_b32_e32 v130, 16, v102
	v_and_b32_e32 v131, 0xffff0000, v102
	v_lshlrev_b32_e32 v132, 16, v103
	v_and_b32_e32 v133, 0xffff0000, v103
	v_pk_fma_f32 v[94:95], v[130:131], v[130:131], v[94:95]
	v_pk_fma_f32 v[134:135], v[132:133], v[132:133], v[134:135]
	v_lshlrev_b32_e32 v144, 16, v118
	v_and_b32_e32 v145, 0xffff0000, v118
	v_lshlrev_b32_e32 v146, 16, v119
	v_and_b32_e32 v147, 0xffff0000, v119
	v_pk_fma_f32 v[148:149], v[144:145], v[144:145], v[148:149]
	v_pk_fma_f32 v[150:151], v[146:147], v[146:147], v[150:151]
	v_lshlrev_b32_e32 v130, 16, v104
	v_and_b32_e32 v131, 0xffff0000, v104
	v_lshlrev_b32_e32 v132, 16, v105
	v_and_b32_e32 v133, 0xffff0000, v105
	v_pk_fma_f32 v[94:95], v[130:131], v[130:131], v[94:95]
	v_pk_fma_f32 v[134:135], v[132:133], v[132:133], v[134:135]
	v_lshlrev_b32_e32 v144, 16, v120
	v_and_b32_e32 v145, 0xffff0000, v120
	v_lshlrev_b32_e32 v146, 16, v121
	v_and_b32_e32 v147, 0xffff0000, v121
	v_pk_fma_f32 v[148:149], v[144:145], v[144:145], v[148:149]
	v_pk_fma_f32 v[150:151], v[146:147], v[146:147], v[150:151]
	v_lshlrev_b32_e32 v130, 16, v106
	v_and_b32_e32 v131, 0xffff0000, v106
	v_lshlrev_b32_e32 v132, 16, v107
	v_and_b32_e32 v133, 0xffff0000, v107
	v_pk_fma_f32 v[94:95], v[130:131], v[130:131], v[94:95]
	v_pk_fma_f32 v[134:135], v[132:133], v[132:133], v[134:135]
	v_lshlrev_b32_e32 v144, 16, v122
	v_and_b32_e32 v145, 0xffff0000, v122
	v_lshlrev_b32_e32 v146, 16, v123
	v_and_b32_e32 v147, 0xffff0000, v123
	v_pk_fma_f32 v[148:149], v[144:145], v[144:145], v[148:149]
	v_pk_fma_f32 v[150:151], v[146:147], v[146:147], v[150:151]
	v_lshlrev_b32_e32 v130, 16, v108
	v_and_b32_e32 v131, 0xffff0000, v108
	v_lshlrev_b32_e32 v132, 16, v109
	v_and_b32_e32 v133, 0xffff0000, v109
	v_pk_fma_f32 v[94:95], v[130:131], v[130:131], v[94:95]
	v_pk_fma_f32 v[134:135], v[132:133], v[132:133], v[134:135]
	v_lshlrev_b32_e32 v144, 16, v124
	v_and_b32_e32 v145, 0xffff0000, v124
	v_lshlrev_b32_e32 v146, 16, v125
	v_and_b32_e32 v147, 0xffff0000, v125
	v_pk_fma_f32 v[148:149], v[144:145], v[144:145], v[148:149]
	v_pk_fma_f32 v[150:151], v[146:147], v[146:147], v[150:151]
	v_lshlrev_b32_e32 v130, 16, v110
	v_and_b32_e32 v131, 0xffff0000, v110
	v_lshlrev_b32_e32 v132, 16, v111
	v_and_b32_e32 v133, 0xffff0000, v111
	v_pk_fma_f32 v[94:95], v[130:131], v[130:131], v[94:95]
	v_pk_fma_f32 v[134:135], v[132:133], v[132:133], v[134:135]
	v_lshlrev_b32_e32 v144, 16, v126
	v_and_b32_e32 v145, 0xffff0000, v126
	v_lshlrev_b32_e32 v146, 16, v127
	v_and_b32_e32 v147, 0xffff0000, v127
	v_pk_fma_f32 v[148:149], v[144:145], v[144:145], v[148:149]
	v_pk_fma_f32 v[150:151], v[146:147], v[146:147], v[150:151]
	v_lshlrev_b32_e32 v130, 16, v112
	v_and_b32_e32 v131, 0xffff0000, v112
	v_lshlrev_b32_e32 v132, 16, v113
	v_and_b32_e32 v133, 0xffff0000, v113
	v_pk_fma_f32 v[94:95], v[130:131], v[130:131], v[94:95]
	v_pk_fma_f32 v[134:135], v[132:133], v[132:133], v[134:135]
	v_lshlrev_b32_e32 v144, 16, v128
	v_and_b32_e32 v145, 0xffff0000, v128
	v_lshlrev_b32_e32 v146, 16, v129
	v_and_b32_e32 v147, 0xffff0000, v129
	v_pk_fma_f32 v[148:149], v[144:145], v[144:145], v[148:149]
	v_pk_fma_f32 v[150:151], v[146:147], v[146:147], v[150:151]
	v_pk_add_f32 v[94:95], v[94:95], v[134:135]
	v_pk_add_f32 v[148:149], v[148:149], v[150:151]
	v_add_f32_e32 v152, v94, v95
	v_add_f32_e32 v154, v148, v149
	v_mov_b32_e32 v156, 0x358637bd
	s_nop 1
	v_add_f32_dpp v152, v152, v152 row_ror:8 row_mask:0xf bank_mask:0xf
	v_add_f32_dpp v154, v154, v154 row_ror:8 row_mask:0xf bank_mask:0xf
	s_nop 1
	v_add_f32_dpp v152, v152, v152 row_ror:4 row_mask:0xf bank_mask:0xf
	v_add_f32_dpp v154, v154, v154 row_ror:4 row_mask:0xf bank_mask:0xf
	s_nop 1
	v_add_f32_dpp v152, v152, v152 row_ror:2 row_mask:0xf bank_mask:0xf
	v_add_f32_dpp v154, v154, v154 row_ror:2 row_mask:0xf bank_mask:0xf
	s_nop 1
	v_add_f32_dpp v152, v152, v152 row_ror:1 row_mask:0xf bank_mask:0xf
	v_add_f32_dpp v154, v154, v154 row_ror:1 row_mask:0xf bank_mask:0xf
	s_nop 1
	v_readlane_b32 s0, v152, 0
	v_readlane_b32 s1, v152, 16
	v_readlane_b32 s2, v152, 32
	v_readlane_b32 s3, v152, 48
	v_readlane_b32 s4, v154, 0
	v_readlane_b32 s5, v154, 16
	v_readlane_b32 s8, v154, 32
	v_readlane_b32 s9, v154, 48
	s_nop 1
	v_mov_b32_e32 v152, s0
	v_mov_b32_e32 v154, s4
	v_add_f32_e32 v152, s1, v152
	v_add_f32_e32 v154, s5, v154
	v_add_f32_e32 v152, s2, v152
	v_add_f32_e32 v154, s8, v154
	v_add_f32_e32 v152, s3, v152
	v_add_f32_e32 v154, s9, v154
	v_fmamk_f32 v152, v152, 0x3a000000, v156
	v_fmamk_f32 v154, v154, 0x3a000000, v156
	v_rsq_f32_e32 v152, v152
	v_rsq_f32_e32 v154, v154
	s_nop 0
	s_waitcnt vmcnt(0)
; __device__ __forceinline__ unsigned cvt_pk_bf16(float lo, float hi) { cvt_f32x2_t v = {lo, hi}; cvt_bf16x2_t b = __builtin_convertvector(v, cvt_bf16x2_t); return __builtin_bit_cast(unsigned, b); }
; __device__ __forceinline__ float bflo(unsigned w) { return __uint_as_float(w << 16); }
; __device__ __forceinline__ float bfhi(unsigned w) { return __uint_as_float(w & 0xffff0000u); }
; __device__ __forceinline__ void rowpass_res(const Frame& F, const Params& p, const float* gpost, const float* gnext, bool first, bool last) {
;     ...
;         for (int u = 0; u < 2; ++u) { const int r = r0 + u; const bf16* hb = HB + (size_t)r * D;
; #pragma unroll
;             for (int j = 0; j < 8; ++j) {
;                 if (first) hv[u][j] = *(const f32x4*)((r < MF ? p.x + (size_t)r * D : p.meta + (size_t)(r - MF) * D) + 4 * F.lane + 256 * j);
;                 else { const u32x2 hw = *(const u32x2*)(hb + 4 * F.lane + 256 * j); hv[u][j] = (f32x4){bflo(hw.x), bfhi(hw.x), bflo(hw.y), bfhi(hw.y)}; } } }
; #pragma unroll
;         for (int u = 0; u < 2; ++u)
; #pragma unroll
;             for (int j = 0; j < 8; ++j) ss[u] += (v[u][j].x * v[u][j].x + v[u][j].y * v[u][j].y) + (v[u][j].z * v[u][j].z + v[u][j].w * v[u][j].w);
;         float rs[2];
; #pragma unroll
;         for (int o = 1; o < 64; o <<= 1) { ss[0] += __shfl_xor(ss[0], o); ss[1] += __shfl_xor(ss[1], o); }
;         rs[0] = rsqrtf(ss[0] * (1.f / D) + EPS); rs[1] = rsqrtf(ss[1] * (1.f / D) + EPS);
;         float ss2[2] = {0.f, 0.f};
; #pragma unroll
;         for (int u = 0; u < 2; ++u) { const int r = r0 + u; bf16* hb = HB + (size_t)r * D;
; #pragma unroll
;             for (int j = 0; j < 8; ++j) { const f32x4 g = *(const f32x4*)(gpost + 4 * F.lane + 256 * j);
;                 v[u][j] = hv[u][j] + v[u][j] * rs[u] * g;
;                 if (last) { if (r < MF) *(f32x4*)(p.out + (size_t)r * D + 4 * F.lane + 256 * j) = v[u][j]; }
;                 else { u32x2 w; w.x = cvt_pk_bf16(v[u][j].x, v[u][j].y); w.y = cvt_pk_bf16(v[u][j].z, v[u][j].w); *(u32x2*)(hb + 4 * F.lane + 256 * j) = w; }
;                 ss2[u] += (v[u][j].x * v[u][j].x + v[u][j].y * v[u][j].y) + (v[u][j].z * v[u][j].z + v[u][j].w * v[u][j].w); } }
	v_lshlrev_b32_e32 v0, 16, v2
	v_and_b32_e32 v1, 0xffff0000, v2
	v_lshlrev_b32_e32 v2, 16, v3
	v_and_b32_e32 v3, 0xffff0000, v3
	v_lshlrev_b32_e32 v4, 16, v6
	v_and_b32_e32 v5, 0xffff0000, v6
	v_lshlrev_b32_e32 v6, 16, v7
	v_and_b32_e32 v7, 0xffff0000, v7
	v_lshlrev_b32_e32 v8, 16, v10
	v_and_b32_e32 v9, 0xffff0000, v10
	v_lshlrev_b32_e32 v10, 16, v11
	v_and_b32_e32 v11, 0xffff0000, v11
	v_lshlrev_b32_e32 v12, 16, v14
	v_and_b32_e32 v13, 0xffff0000, v14
	v_lshlrev_b32_e32 v14, 16, v15
	v_and_b32_e32 v15, 0xffff0000, v15
	v_lshlrev_b32_e32 v16, 16, v18
	v_and_b32_e32 v17, 0xffff0000, v18
	v_lshlrev_b32_e32 v18, 16, v19
	v_and_b32_e32 v19, 0xffff0000, v19
	v_lshlrev_b32_e32 v20, 16, v22
	v_and_b32_e32 v21, 0xffff0000, v22
	v_lshlrev_b32_e32 v22, 16, v23
	v_and_b32_e32 v23, 0xffff0000, v23
	v_lshlrev_b32_e32 v24, 16, v26
	v_and_b32_e32 v25, 0xffff0000, v26
	v_lshlrev_b32_e32 v26, 16, v27
	v_and_b32_e32 v27, 0xffff0000, v27
	v_lshlrev_b32_e32 v28, 16, v30
	v_and_b32_e32 v29, 0xffff0000, v30
	v_lshlrev_b32_e32 v30, 16, v31
	v_and_b32_e32 v31, 0xffff0000, v31
	v_lshlrev_b32_e32 v32, 16, v34
	v_and_b32_e32 v33, 0xffff0000, v34
	v_lshlrev_b32_e32 v34, 16, v35
	v_and_b32_e32 v35, 0xffff0000, v35
	v_lshlrev_b32_e32 v36, 16, v38
	v_and_b32_e32 v37, 0xffff0000, v38
	v_lshlrev_b32_e32 v38, 16, v39
	v_and_b32_e32 v39, 0xffff0000, v39
	v_lshlrev_b32_e32 v40, 16, v42
	v_and_b32_e32 v41, 0xffff0000, v42
	v_lshlrev_b32_e32 v42, 16, v43
	v_and_b32_e32 v43, 0xffff0000, v43
	v_lshlrev_b32_e32 v44, 16, v46
	v_and_b32_e32 v45, 0xffff0000, v46
	v_lshlrev_b32_e32 v46, 16, v47
	v_and_b32_e32 v47, 0xffff0000, v47
	v_lshlrev_b32_e32 v48, 16, v50
	v_and_b32_e32 v49, 0xffff0000, v50
	v_lshlrev_b32_e32 v50, 16, v51
	v_and_b32_e32 v51, 0xffff0000, v51
	v_lshlrev_b32_e32 v52, 16, v54
	v_and_b32_e32 v53, 0xffff0000, v54
	v_lshlrev_b32_e32 v54, 16, v55
	v_and_b32_e32 v55, 0xffff0000, v55
	v_lshlrev_b32_e32 v56, 16, v58
	v_and_b32_e32 v57, 0xffff0000, v58
	v_lshlrev_b32_e32 v58, 16, v59
	v_and_b32_e32 v59, 0xffff0000, v59
	v_lshlrev_b32_e32 v60, 16, v62
	v_and_b32_e32 v61, 0xffff0000, v62
	v_lshlrev_b32_e32 v62, 16, v63
	v_and_b32_e32 v63, 0xffff0000, v63
	s_cmp_lg_u64 s[90:91], 0
	s_cbranch_scc1 .Lrp9_notlast
	s_cmpk_lt_i32 s6, 0x4000
	s_cbranch_scc0 .Lrp9_last_nostore
	v_add_co_u32_e32 v158, vcc, 0xfffff000, v86
	s_nop 1
	v_addc_co_u32_e32 v159, vcc, -1, v87, vcc
	v_add_co_u32_e32 v160, vcc, 0x1000, v86
	s_nop 1
	v_addc_co_u32_e32 v161, vcc, 0, v87, vcc
	v_lshlrev_b32_e32 v130, 16, v98
	v_and_b32_e32 v131, 0xffff0000, v98
	v_lshlrev_b32_e32 v132, 16, v99
	v_and_b32_e32 v133, 0xffff0000, v99
	v_pk_mul_f32 v[130:131], v[152:153], v[130:131] op_sel_hi:[0,1]
	v_pk_mul_f32 v[132:133], v[152:153], v[132:133] op_sel_hi:[0,1]
	v_pk_fma_f32 v[0:1], v[130:131], v[204:205], v[0:1]
	v_pk_fma_f32 v[2:3], v[132:133], v[206:207], v[2:3]
	v_pk_mul_f32 v[94:95], v[0:1], v[0:1]
	v_pk_mul_f32 v[134:135], v[2:3], v[2:3]
	global_store_dwordx4 v[158:159], v[0:3], off offset:-4096
	v_lshlrev_b32_e32 v144, 16, v114
	v_and_b32_e32 v145, 0xffff0000, v114
	v_lshlrev_b32_e32 v146, 16, v115
	v_and_b32_e32 v147, 0xffff0000, v115
	v_pk_mul_f32 v[144:145], v[154:155], v[144:145] op_sel_hi:[0,1]
	v_pk_mul_f32 v[146:147], v[154:155], v[146:147] op_sel_hi:[0,1]
	v_pk_fma_f32 v[32:33], v[144:145], v[204:205], v[32:33]
	v_pk_fma_f32 v[34:35], v[146:147], v[206:207], v[34:35]
	v_pk_mul_f32 v[148:149], v[32:33], v[32:33]
	v_pk_mul_f32 v[150:151], v[34:35], v[34:35]
	global_store_dwordx4 v[86:87], v[32:35], off
	v_lshlrev_b32_e32 v130, 16, v100
	v_and_b32_e32 v131, 0xffff0000, v100
	v_lshlrev_b32_e32 v132, 16, v101
	v_and_b32_e32 v133, 0xffff0000, v101
	v_pk_mul_f32 v[130:131], v[152:153], v[130:131] op_sel_hi:[0,1]
	v_pk_mul_f32 v[132:133], v[152:153], v[132:133] op_sel_hi:[0,1]
	v_pk_fma_f32 v[4:5], v[130:131], v[208:209], v[4:5]
	v_pk_fma_f32 v[6:7], v[132:133], v[210:211], v[6:7]
	v_pk_fma_f32 v[94:95], v[4:5], v[4:5], v[94:95]
	v_pk_fma_f32 v[134:135], v[6:7], v[6:7], v[134:135]
	global_store_dwordx4 v[158:159], v[4:7], off offset:-3072
	v_lshlrev_b32_e32 v144, 16, v116
	v_and_b32_e32 v145, 0xffff0000, v116
	v_lshlrev_b32_e32 v146, 16, v117
	v_and_b32_e32 v147, 0xffff0000, v117
	v_pk_mul_f32 v[144:145], v[154:155], v[144:145] op_sel_hi:[0,1]
	v_pk_mul_f32 v[146:147], v[154:155], v[146:147] op_sel_hi:[0,1]
	v_pk_fma_f32 v[36:37], v[144:145], v[208:209], v[36:37]
	v_pk_fma_f32 v[38:39], v[146:147], v[210:211], v[38:39]
	v_pk_fma_f32 v[148:149], v[36:37], v[36:37], v[148:149]
	v_pk_fma_f32 v[150:151], v[38:39], v[38:39], v[150:151]
	global_store_dwordx4 v[86:87], v[36:39], off offset:1024
	v_lshlrev_b32_e32 v130, 16, v102
	v_and_b32_e32 v131, 0xffff0000, v102
	v_lshlrev_b32_e32 v132, 16, v103
	v_and_b32_e32 v133, 0xffff0000, v103
	v_pk_mul_f32 v[130:131], v[152:153], v[130:131] op_sel_hi:[0,1]
	v_pk_mul_f32 v[132:133], v[152:153], v[132:133] op_sel_hi:[0,1]
	v_pk_fma_f32 v[8:9], v[130:131], v[212:213], v[8:9]
	v_pk_fma_f32 v[10:11], v[132:133], v[214:215], v[10:11]
	v_pk_fma_f32 v[94:95], v[8:9], v[8:9], v[94:95]
	v_pk_fma_f32 v[134:135], v[10:11], v[10:11], v[134:135]
	global_store_dwordx4 v[158:159], v[8:11], off offset:-2048
	v_lshlrev_b32_e32 v144, 16, v118
	v_and_b32_e32 v145, 0xffff0000, v118
	v_lshlrev_b32_e32 v146, 16, v119
	v_and_b32_e32 v147, 0xffff0000, v119
	v_pk_mul_f32 v[144:145], v[154:155], v[144:145] op_sel_hi:[0,1]
	v_pk_mul_f32 v[146:147], v[154:155], v[146:147] op_sel_hi:[0,1]
	v_pk_fma_f32 v[40:41], v[144:145], v[212:213], v[40:41]
	v_pk_fma_f32 v[42:43], v[146:147], v[214:215], v[42:43]
	v_pk_fma_f32 v[148:149], v[40:41], v[40:41], v[148:149]
	v_pk_fma_f32 v[150:151], v[42:43], v[42:43], v[150:151]
; __device__ __forceinline__ unsigned cvt_pk_bf16(float lo, float hi) { cvt_f32x2_t v = {lo, hi}; cvt_bf16x2_t b = __builtin_convertvector(v, cvt_bf16x2_t); return __builtin_bit_cast(unsigned, b); }
; __device__ __forceinline__ void rowpass_res(const Frame& F, const Params& p, const float* gpost, const float* gnext, bool first, bool last) {
;     ...
;         for (int u = 0; u < 2; ++u) { const int r = r0 + u; bf16* hb = HB + (size_t)r * D;
; #pragma unroll
;             for (int j = 0; j < 8; ++j) { const f32x4 g = *(const f32x4*)(gpost + 4 * F.lane + 256 * j);
;                 v[u][j] = hv[u][j] + v[u][j] * rs[u] * g;
;                 if (last) { if (r < MF) *(f32x4*)(p.out + (size_t)r * D + 4 * F.lane + 256 * j) = v[u][j]; }
;                 else { u32x2 w; w.x = cvt_pk_bf16(v[u][j].x, v[u][j].y); w.y = cvt_pk_bf16(v[u][j].z, v[u][j].w); *(u32x2*)(hb + 4 * F.lane + 256 * j) = w; }
;                 ss2[u] += (v[u][j].x * v[u][j].x + v[u][j].y * v[u][j].y) + (v[u][j].z * v[u][j].z + v[u][j].w * v[u][j].w); } }
	global_store_dwordx4 v[86:87], v[40:43], off offset:2048
	v_lshlrev_b32_e32 v130, 16, v104
	v_and_b32_e32 v131, 0xffff0000, v104
	v_lshlrev_b32_e32 v132, 16, v105
	v_and_b32_e32 v133, 0xffff0000, v105
	v_pk_mul_f32 v[130:131], v[152:153], v[130:131] op_sel_hi:[0,1]
	v_pk_mul_f32 v[132:133], v[152:153], v[132:133] op_sel_hi:[0,1]
	v_pk_fma_f32 v[12:13], v[130:131], v[216:217], v[12:13]
	v_pk_fma_f32 v[14:15], v[132:133], v[218:219], v[14:15]
	v_pk_fma_f32 v[94:95], v[12:13], v[12:13], v[94:95]
	v_pk_fma_f32 v[134:135], v[14:15], v[14:15], v[134:135]
	global_store_dwordx4 v[158:159], v[12:15], off offset:-1024
	v_lshlrev_b32_e32 v144, 16, v120
	v_and_b32_e32 v145, 0xffff0000, v120
	v_lshlrev_b32_e32 v146, 16, v121
	v_and_b32_e32 v147, 0xffff0000, v121
	v_pk_mul_f32 v[144:145], v[154:155], v[144:145] op_sel_hi:[0,1]
	v_pk_mul_f32 v[146:147], v[154:155], v[146:147] op_sel_hi:[0,1]
	v_pk_fma_f32 v[44:45], v[144:145], v[216:217], v[44:45]
	v_pk_fma_f32 v[46:47], v[146:147], v[218:219], v[46:47]
	v_pk_fma_f32 v[148:149], v[44:45], v[44:45], v[148:149]
	v_pk_fma_f32 v[150:151], v[46:47], v[46:47], v[150:151]
	global_store_dwordx4 v[86:87], v[44:47], off offset:3072
	v_lshlrev_b32_e32 v130, 16, v106
	v_and_b32_e32 v131, 0xffff0000, v106
	v_lshlrev_b32_e32 v132, 16, v107
	v_and_b32_e32 v133, 0xffff0000, v107
	v_pk_mul_f32 v[130:131], v[152:153], v[130:131] op_sel_hi:[0,1]
	v_pk_mul_f32 v[132:133], v[152:153], v[132:133] op_sel_hi:[0,1]
	v_pk_fma_f32 v[16:17], v[130:131], v[220:221], v[16:17]
	v_pk_fma_f32 v[18:19], v[132:133], v[222:223], v[18:19]
	v_pk_fma_f32 v[94:95], v[16:17], v[16:17], v[94:95]
	v_pk_fma_f32 v[134:135], v[18:19], v[18:19], v[134:135]
	global_store_dwordx4 v[86:87], v[16:19], off offset:-4096
	v_lshlrev_b32_e32 v144, 16, v122
	v_and_b32_e32 v145, 0xffff0000, v122
	v_lshlrev_b32_e32 v146, 16, v123
	v_and_b32_e32 v147, 0xffff0000, v123
	v_pk_mul_f32 v[144:145], v[154:155], v[144:145] op_sel_hi:[0,1]
	v_pk_mul_f32 v[146:147], v[154:155], v[146:147] op_sel_hi:[0,1]
	v_pk_fma_f32 v[48:49], v[144:145], v[220:221], v[48:49]
	v_pk_fma_f32 v[50:51], v[146:147], v[222:223], v[50:51]
	v_pk_fma_f32 v[148:149], v[48:49], v[48:49], v[148:149]
	v_pk_fma_f32 v[150:151], v[50:51], v[50:51], v[150:151]
	global_store_dwordx4 v[160:161], v[48:51], off
	v_lshlrev_b32_e32 v130, 16, v108
	v_and_b32_e32 v131, 0xffff0000, v108
	v_lshlrev_b32_e32 v132, 16, v109
	v_and_b32_e32 v133, 0xffff0000, v109
	v_pk_mul_f32 v[130:131], v[152:153], v[130:131] op_sel_hi:[0,1]
	v_pk_mul_f32 v[132:133], v[152:153], v[132:133] op_sel_hi:[0,1]
	v_pk_fma_f32 v[20:21], v[130:131], v[224:225], v[20:21]
	v_pk_fma_f32 v[22:23], v[132:133], v[226:227], v[22:23]
	v_pk_fma_f32 v[94:95], v[20:21], v[20:21], v[94:95]
	v_pk_fma_f32 v[134:135], v[22:23], v[22:23], v[134:135]
	global_store_dwordx4 v[86:87], v[20:23], off offset:-3072
	v_lshlrev_b32_e32 v144, 16, v124
	v_and_b32_e32 v145, 0xffff0000, v124
	v_lshlrev_b32_e32 v146, 16, v125
	v_and_b32_e32 v147, 0xffff0000, v125
	v_pk_mul_f32 v[144:145], v[154:155], v[144:145] op_sel_hi:[0,1]
	v_pk_mul_f32 v[146:147], v[154:155], v[146:147] op_sel_hi:[0,1]
	v_pk_fma_f32 v[52:53], v[144:145], v[224:225], v[52:53]
	v_pk_fma_f32 v[54:55], v[146:147], v[226:227], v[54:55]
	v_pk_fma_f32 v[148:149], v[52:53], v[52:53], v[148:149]
	v_pk_fma_f32 v[150:151], v[54:55], v[54:55], v[150:151]
	global_store_dwordx4 v[160:161], v[52:55], off offset:1024
	v_lshlrev_b32_e32 v130, 16, v110
	v_and_b32_e32 v131, 0xffff0000, v110
	v_lshlrev_b32_e32 v132, 16, v111
	v_and_b32_e32 v133, 0xffff0000, v111
	v_pk_mul_f32 v[130:131], v[152:153], v[130:131] op_sel_hi:[0,1]
	v_pk_mul_f32 v[132:133], v[152:153], v[132:133] op_sel_hi:[0,1]
	v_pk_fma_f32 v[24:25], v[130:131], v[228:229], v[24:25]
	v_pk_fma_f32 v[26:27], v[132:133], v[230:231], v[26:27]
	v_pk_fma_f32 v[94:95], v[24:25], v[24:25], v[94:95]
	v_pk_fma_f32 v[134:135], v[26:27], v[26:27], v[134:135]
	global_store_dwordx4 v[86:87], v[24:27], off offset:-2048
	v_lshlrev_b32_e32 v144, 16, v126
	v_and_b32_e32 v145, 0xffff0000, v126
	v_lshlrev_b32_e32 v146, 16, v127
	v_and_b32_e32 v147, 0xffff0000, v127
	v_pk_mul_f32 v[144:145], v[154:155], v[144:145] op_sel_hi:[0,1]
	v_pk_mul_f32 v[146:147], v[154:155], v[146:147] op_sel_hi:[0,1]
	v_pk_fma_f32 v[56:57], v[144:145], v[228:229], v[56:57]
	v_pk_fma_f32 v[58:59], v[146:147], v[230:231], v[58:59]
	v_pk_fma_f32 v[148:149], v[56:57], v[56:57], v[148:149]
	v_pk_fma_f32 v[150:151], v[58:59], v[58:59], v[150:151]
	global_store_dwordx4 v[160:161], v[56:59], off offset:2048
	v_lshlrev_b32_e32 v130, 16, v112
	v_and_b32_e32 v131, 0xffff0000, v112
	v_lshlrev_b32_e32 v132, 16, v113
	v_and_b32_e32 v133, 0xffff0000, v113
	v_pk_mul_f32 v[130:131], v[152:153], v[130:131] op_sel_hi:[0,1]
	v_pk_mul_f32 v[132:133], v[152:153], v[132:133] op_sel_hi:[0,1]
	v_pk_fma_f32 v[28:29], v[130:131], v[232:233], v[28:29]
	v_pk_fma_f32 v[30:31], v[132:133], v[234:235], v[30:31]
	v_pk_fma_f32 v[94:95], v[28:29], v[28:29], v[94:95]
	v_pk_fma_f32 v[134:135], v[30:31], v[30:31], v[134:135]
	global_store_dwordx4 v[86:87], v[28:31], off offset:-1024
	v_lshlrev_b32_e32 v144, 16, v128
	v_and_b32_e32 v145, 0xffff0000, v128
	v_lshlrev_b32_e32 v146, 16, v129
	v_and_b32_e32 v147, 0xffff0000, v129
	v_pk_mul_f32 v[144:145], v[154:155], v[144:145] op_sel_hi:[0,1]
	v_pk_mul_f32 v[146:147], v[154:155], v[146:147] op_sel_hi:[0,1]
	v_pk_fma_f32 v[60:61], v[144:145], v[232:233], v[60:61]
	v_pk_fma_f32 v[62:63], v[146:147], v[234:235], v[62:63]
	v_pk_fma_f32 v[148:149], v[60:61], v[60:61], v[148:149]
	v_pk_fma_f32 v[150:151], v[62:63], v[62:63], v[150:151]
	global_store_dwordx4 v[160:161], v[60:63], off offset:3072
	s_branch .Lrp9_out_done
; __device__ __forceinline__ unsigned cvt_pk_bf16(float lo, float hi) { cvt_f32x2_t v = {lo, hi}; cvt_bf16x2_t b = __builtin_convertvector(v, cvt_bf16x2_t); return __builtin_bit_cast(unsigned, b); }
; __device__ __forceinline__ void rowpass_res(const Frame& F, const Params& p, const float* gpost, const float* gnext, bool first, bool last) {
;     ...
;         for (int u = 0; u < 2; ++u) { const int r = r0 + u; bf16* hb = HB + (size_t)r * D;
; #pragma unroll
;             for (int j = 0; j < 8; ++j) { const f32x4 g = *(const f32x4*)(gpost + 4 * F.lane + 256 * j);
;                 v[u][j] = hv[u][j] + v[u][j] * rs[u] * g;
;                 if (last) { if (r < MF) *(f32x4*)(p.out + (size_t)r * D + 4 * F.lane + 256 * j) = v[u][j]; }
;                 else { u32x2 w; w.x = cvt_pk_bf16(v[u][j].x, v[u][j].y); w.y = cvt_pk_bf16(v[u][j].z, v[u][j].w); *(u32x2*)(hb + 4 * F.lane + 256 * j) = w; }
;                 ss2[u] += (v[u][j].x * v[u][j].x + v[u][j].y * v[u][j].y) + (v[u][j].z * v[u][j].z + v[u][j].w * v[u][j].w); } }
.Lrp9_last_nostore:
	v_lshlrev_b32_e32 v130, 16, v98
	v_and_b32_e32 v131, 0xffff0000, v98
	v_lshlrev_b32_e32 v132, 16, v99
	v_and_b32_e32 v133, 0xffff0000, v99
	v_pk_mul_f32 v[130:131], v[152:153], v[130:131] op_sel_hi:[0,1]
	v_pk_mul_f32 v[132:133], v[152:153], v[132:133] op_sel_hi:[0,1]
	v_pk_fma_f32 v[0:1], v[130:131], v[204:205], v[0:1]
	v_pk_fma_f32 v[2:3], v[132:133], v[206:207], v[2:3]
	v_pk_mul_f32 v[94:95], v[0:1], v[0:1]
	v_pk_mul_f32 v[134:135], v[2:3], v[2:3]
	v_lshlrev_b32_e32 v144, 16, v114
	v_and_b32_e32 v145, 0xffff0000, v114
	v_lshlrev_b32_e32 v146, 16, v115
	v_and_b32_e32 v147, 0xffff0000, v115
	v_pk_mul_f32 v[144:145], v[154:155], v[144:145] op_sel_hi:[0,1]
	v_pk_mul_f32 v[146:147], v[154:155], v[146:147] op_sel_hi:[0,1]
	v_pk_fma_f32 v[32:33], v[144:145], v[204:205], v[32:33]
	v_pk_fma_f32 v[34:35], v[146:147], v[206:207], v[34:35]
	v_pk_mul_f32 v[148:149], v[32:33], v[32:33]
	v_pk_mul_f32 v[150:151], v[34:35], v[34:35]
	v_lshlrev_b32_e32 v130, 16, v100
	v_and_b32_e32 v131, 0xffff0000, v100
	v_lshlrev_b32_e32 v132, 16, v101
	v_and_b32_e32 v133, 0xffff0000, v101
	v_pk_mul_f32 v[130:131], v[152:153], v[130:131] op_sel_hi:[0,1]
	v_pk_mul_f32 v[132:133], v[152:153], v[132:133] op_sel_hi:[0,1]
	v_pk_fma_f32 v[4:5], v[130:131], v[208:209], v[4:5]
	v_pk_fma_f32 v[6:7], v[132:133], v[210:211], v[6:7]
	v_pk_fma_f32 v[94:95], v[4:5], v[4:5], v[94:95]
	v_pk_fma_f32 v[134:135], v[6:7], v[6:7], v[134:135]
	v_lshlrev_b32_e32 v144, 16, v116
	v_and_b32_e32 v145, 0xffff0000, v116
	v_lshlrev_b32_e32 v146, 16, v117
	v_and_b32_e32 v147, 0xffff0000, v117
	v_pk_mul_f32 v[144:145], v[154:155], v[144:145] op_sel_hi:[0,1]
	v_pk_mul_f32 v[146:147], v[154:155], v[146:147] op_sel_hi:[0,1]
	v_pk_fma_f32 v[36:37], v[144:145], v[208:209], v[36:37]
	v_pk_fma_f32 v[38:39], v[146:147], v[210:211], v[38:39]
	v_pk_fma_f32 v[148:149], v[36:37], v[36:37], v[148:149]
	v_pk_fma_f32 v[150:151], v[38:39], v[38:39], v[150:151]
	v_lshlrev_b32_e32 v130, 16, v102
	v_and_b32_e32 v131, 0xffff0000, v102
	v_lshlrev_b32_e32 v132, 16, v103
	v_and_b32_e32 v133, 0xffff0000, v103
	v_pk_mul_f32 v[130:131], v[152:153], v[130:131] op_sel_hi:[0,1]
	v_pk_mul_f32 v[132:133], v[152:153], v[132:133] op_sel_hi:[0,1]
	v_pk_fma_f32 v[8:9], v[130:131], v[212:213], v[8:9]
	v_pk_fma_f32 v[10:11], v[132:133], v[214:215], v[10:11]
	v_pk_fma_f32 v[94:95], v[8:9], v[8:9], v[94:95]
	v_pk_fma_f32 v[134:135], v[10:11], v[10:11], v[134:135]
	v_lshlrev_b32_e32 v144, 16, v118
	v_and_b32_e32 v145, 0xffff0000, v118
	v_lshlrev_b32_e32 v146, 16, v119
	v_and_b32_e32 v147, 0xffff0000, v119
	v_pk_mul_f32 v[144:145], v[154:155], v[144:145] op_sel_hi:[0,1]
	v_pk_mul_f32 v[146:147], v[154:155], v[146:147] op_sel_hi:[0,1]
	v_pk_fma_f32 v[40:41], v[144:145], v[212:213], v[40:41]
	v_pk_fma_f32 v[42:43], v[146:147], v[214:215], v[42:43]
	v_pk_fma_f32 v[148:149], v[40:41], v[40:41], v[148:149]
	v_pk_fma_f32 v[150:151], v[42:43], v[42:43], v[150:151]
	v_lshlrev_b32_e32 v130, 16, v104
	v_and_b32_e32 v131, 0xffff0000, v104
	v_lshlrev_b32_e32 v132, 16, v105
	v_and_b32_e32 v133, 0xffff0000, v105
	v_pk_mul_f32 v[130:131], v[152:153], v[130:131] op_sel_hi:[0,1]
	v_pk_mul_f32 v[132:133], v[152:153], v[132:133] op_sel_hi:[0,1]
	v_pk_fma_f32 v[12:13], v[130:131], v[216:217], v[12:13]
	v_pk_fma_f32 v[14:15], v[132:133], v[218:219], v[14:15]
	v_pk_fma_f32 v[94:95], v[12:13], v[12:13], v[94:95]
	v_pk_fma_f32 v[134:135], v[14:15], v[14:15], v[134:135]
	v_lshlrev_b32_e32 v144, 16, v120
	v_and_b32_e32 v145, 0xffff0000, v120
	v_lshlrev_b32_e32 v146, 16, v121
	v_and_b32_e32 v147, 0xffff0000, v121
	v_pk_mul_f32 v[144:145], v[154:155], v[144:145] op_sel_hi:[0,1]
	v_pk_mul_f32 v[146:147], v[154:155], v[146:147] op_sel_hi:[0,1]
	v_pk_fma_f32 v[44:45], v[144:145], v[216:217], v[44:45]
	v_pk_fma_f32 v[46:47], v[146:147], v[218:219], v[46:47]
	v_pk_fma_f32 v[148:149], v[44:45], v[44:45], v[148:149]
	v_pk_fma_f32 v[150:151], v[46:47], v[46:47], v[150:151]
	v_lshlrev_b32_e32 v130, 16, v106
	v_and_b32_e32 v131, 0xffff0000, v106
	v_lshlrev_b32_e32 v132, 16, v107
	v_and_b32_e32 v133, 0xffff0000, v107
	v_pk_mul_f32 v[130:131], v[152:153], v[130:131] op_sel_hi:[0,1]
	v_pk_mul_f32 v[132:133], v[152:153], v[132:133] op_sel_hi:[0,1]
	v_pk_fma_f32 v[16:17], v[130:131], v[220:221], v[16:17]
	v_pk_fma_f32 v[18:19], v[132:133], v[222:223], v[18:19]
	v_pk_fma_f32 v[94:95], v[16:17], v[16:17], v[94:95]
	v_pk_fma_f32 v[134:135], v[18:19], v[18:19], v[134:135]
	v_lshlrev_b32_e32 v144, 16, v122
	v_and_b32_e32 v145, 0xffff0000, v122
	v_lshlrev_b32_e32 v146, 16, v123
	v_and_b32_e32 v147, 0xffff0000, v123
	v_pk_mul_f32 v[144:145], v[154:155], v[144:145] op_sel_hi:[0,1]
	v_pk_mul_f32 v[146:147], v[154:155], v[146:147] op_sel_hi:[0,1]
	v_pk_fma_f32 v[48:49], v[144:145], v[220:221], v[48:49]
	v_pk_fma_f32 v[50:51], v[146:147], v[222:223], v[50:51]
	v_pk_fma_f32 v[148:149], v[48:49], v[48:49], v[148:149]
	v_pk_fma_f32 v[150:151], v[50:51], v[50:51], v[150:151]
	v_lshlrev_b32_e32 v130, 16, v108
	v_and_b32_e32 v131, 0xffff0000, v108
	v_lshlrev_b32_e32 v132, 16, v109
	v_and_b32_e32 v133, 0xffff0000, v109
	v_pk_mul_f32 v[130:131], v[152:153], v[130:131] op_sel_hi:[0,1]
	v_pk_mul_f32 v[132:133], v[152:153], v[132:133] op_sel_hi:[0,1]
	v_pk_fma_f32 v[20:21], v[130:131], v[224:225], v[20:21]
	v_pk_fma_f32 v[22:23], v[132:133], v[226:227], v[22:23]
	v_pk_fma_f32 v[94:95], v[20:21], v[20:21], v[94:95]
	v_pk_fma_f32 v[134:135], v[22:23], v[22:23], v[134:135]
	v_lshlrev_b32_e32 v144, 16, v124
	v_and_b32_e32 v145, 0xffff0000, v124
	v_lshlrev_b32_e32 v146, 16, v125
	v_and_b32_e32 v147, 0xffff0000, v125
	v_pk_mul_f32 v[144:145], v[154:155], v[144:145] op_sel_hi:[0,1]
; __device__ __forceinline__ unsigned cvt_pk_bf16(float lo, float hi) { cvt_f32x2_t v = {lo, hi}; cvt_bf16x2_t b = __builtin_convertvector(v, cvt_bf16x2_t); return __builtin_bit_cast(unsigned, b); }
; __device__ __forceinline__ void rowpass_res(const Frame& F, const Params& p, const float* gpost, const float* gnext, bool first, bool last) {
;     ...
;         for (int u = 0; u < 2; ++u) { const int r = r0 + u; bf16* hb = HB + (size_t)r * D;
; #pragma unroll
;             for (int j = 0; j < 8; ++j) { const f32x4 g = *(const f32x4*)(gpost + 4 * F.lane + 256 * j);
;                 v[u][j] = hv[u][j] + v[u][j] * rs[u] * g;
;                 if (last) { if (r < MF) *(f32x4*)(p.out + (size_t)r * D + 4 * F.lane + 256 * j) = v[u][j]; }
;                 else { u32x2 w; w.x = cvt_pk_bf16(v[u][j].x, v[u][j].y); w.y = cvt_pk_bf16(v[u][j].z, v[u][j].w); *(u32x2*)(hb + 4 * F.lane + 256 * j) = w; }
;                 ss2[u] += (v[u][j].x * v[u][j].x + v[u][j].y * v[u][j].y) + (v[u][j].z * v[u][j].z + v[u][j].w * v[u][j].w); } }
	v_pk_mul_f32 v[146:147], v[154:155], v[146:147] op_sel_hi:[0,1]
	v_pk_fma_f32 v[52:53], v[144:145], v[224:225], v[52:53]
	v_pk_fma_f32 v[54:55], v[146:147], v[226:227], v[54:55]
	v_pk_fma_f32 v[148:149], v[52:53], v[52:53], v[148:149]
	v_pk_fma_f32 v[150:151], v[54:55], v[54:55], v[150:151]
	v_lshlrev_b32_e32 v130, 16, v110
	v_and_b32_e32 v131, 0xffff0000, v110
	v_lshlrev_b32_e32 v132, 16, v111
	v_and_b32_e32 v133, 0xffff0000, v111
	v_pk_mul_f32 v[130:131], v[152:153], v[130:131] op_sel_hi:[0,1]
	v_pk_mul_f32 v[132:133], v[152:153], v[132:133] op_sel_hi:[0,1]
	v_pk_fma_f32 v[24:25], v[130:131], v[228:229], v[24:25]
	v_pk_fma_f32 v[26:27], v[132:133], v[230:231], v[26:27]
	v_pk_fma_f32 v[94:95], v[24:25], v[24:25], v[94:95]
	v_pk_fma_f32 v[134:135], v[26:27], v[26:27], v[134:135]
	v_lshlrev_b32_e32 v144, 16, v126
	v_and_b32_e32 v145, 0xffff0000, v126
	v_lshlrev_b32_e32 v146, 16, v127
	v_and_b32_e32 v147, 0xffff0000, v127
	v_pk_mul_f32 v[144:145], v[154:155], v[144:145] op_sel_hi:[0,1]
	v_pk_mul_f32 v[146:147], v[154:155], v[146:147] op_sel_hi:[0,1]
	v_pk_fma_f32 v[56:57], v[144:145], v[228:229], v[56:57]
	v_pk_fma_f32 v[58:59], v[146:147], v[230:231], v[58:59]
	v_pk_fma_f32 v[148:149], v[56:57], v[56:57], v[148:149]
	v_pk_fma_f32 v[150:151], v[58:59], v[58:59], v[150:151]
	v_lshlrev_b32_e32 v130, 16, v112
	v_and_b32_e32 v131, 0xffff0000, v112
	v_lshlrev_b32_e32 v132, 16, v113
	v_and_b32_e32 v133, 0xffff0000, v113
	v_pk_mul_f32 v[130:131], v[152:153], v[130:131] op_sel_hi:[0,1]
	v_pk_mul_f32 v[132:133], v[152:153], v[132:133] op_sel_hi:[0,1]
	v_pk_fma_f32 v[28:29], v[130:131], v[232:233], v[28:29]
	v_pk_fma_f32 v[30:31], v[132:133], v[234:235], v[30:31]
	v_pk_fma_f32 v[94:95], v[28:29], v[28:29], v[94:95]
	v_pk_fma_f32 v[134:135], v[30:31], v[30:31], v[134:135]
	v_lshlrev_b32_e32 v144, 16, v128
	v_and_b32_e32 v145, 0xffff0000, v128
	v_lshlrev_b32_e32 v146, 16, v129
	v_and_b32_e32 v147, 0xffff0000, v129
	v_pk_mul_f32 v[144:145], v[154:155], v[144:145] op_sel_hi:[0,1]
	v_pk_mul_f32 v[146:147], v[154:155], v[146:147] op_sel_hi:[0,1]
	v_pk_fma_f32 v[60:61], v[144:145], v[232:233], v[60:61]
	v_pk_fma_f32 v[62:63], v[146:147], v[234:235], v[62:63]
	v_pk_fma_f32 v[148:149], v[60:61], v[60:61], v[148:149]
	v_pk_fma_f32 v[150:151], v[62:63], v[62:63], v[150:151]
	s_branch .Lrp9_out_done
.Lrp9_notlast:
	v_lshlrev_b32_e32 v130, 16, v98
	v_and_b32_e32 v131, 0xffff0000, v98
	v_lshlrev_b32_e32 v132, 16, v99
	v_and_b32_e32 v133, 0xffff0000, v99
	v_pk_mul_f32 v[130:131], v[152:153], v[130:131] op_sel_hi:[0,1]
	v_pk_mul_f32 v[132:133], v[152:153], v[132:133] op_sel_hi:[0,1]
	v_pk_fma_f32 v[0:1], v[130:131], v[204:205], v[0:1]
	v_pk_fma_f32 v[2:3], v[132:133], v[206:207], v[2:3]
	v_pk_mul_f32 v[94:95], v[0:1], v[0:1]
	v_pk_mul_f32 v[134:135], v[2:3], v[2:3]
	v_cvt_pk_bf16_f32 v130, v0, v1
	v_cvt_pk_bf16_f32 v131, v2, v3
	global_store_dwordx2 v[88:89], v[130:131], off offset:-3584
	v_lshlrev_b32_e32 v144, 16, v114
	v_and_b32_e32 v145, 0xffff0000, v114
	v_lshlrev_b32_e32 v146, 16, v115
	v_and_b32_e32 v147, 0xffff0000, v115
	v_pk_mul_f32 v[144:145], v[154:155], v[144:145] op_sel_hi:[0,1]
	v_pk_mul_f32 v[146:147], v[154:155], v[146:147] op_sel_hi:[0,1]
	v_pk_fma_f32 v[32:33], v[144:145], v[204:205], v[32:33]
	v_pk_fma_f32 v[34:35], v[146:147], v[206:207], v[34:35]
	v_pk_mul_f32 v[148:149], v[32:33], v[32:33]
	v_pk_mul_f32 v[150:151], v[34:35], v[34:35]
	v_cvt_pk_bf16_f32 v144, v32, v33
	v_cvt_pk_bf16_f32 v145, v34, v35
	global_store_dwordx2 v[84:85], v[144:145], off offset:-3584
	v_lshlrev_b32_e32 v130, 16, v100
	v_and_b32_e32 v131, 0xffff0000, v100
	v_lshlrev_b32_e32 v132, 16, v101
	v_and_b32_e32 v133, 0xffff0000, v101
	v_pk_mul_f32 v[130:131], v[152:153], v[130:131] op_sel_hi:[0,1]
	v_pk_mul_f32 v[132:133], v[152:153], v[132:133] op_sel_hi:[0,1]
	v_pk_fma_f32 v[4:5], v[130:131], v[208:209], v[4:5]
	v_pk_fma_f32 v[6:7], v[132:133], v[210:211], v[6:7]
	v_pk_fma_f32 v[94:95], v[4:5], v[4:5], v[94:95]
	v_pk_fma_f32 v[134:135], v[6:7], v[6:7], v[134:135]
	v_cvt_pk_bf16_f32 v130, v4, v5
	v_cvt_pk_bf16_f32 v131, v6, v7
	global_store_dwordx2 v[88:89], v[130:131], off offset:-3072
	v_lshlrev_b32_e32 v144, 16, v116
	v_and_b32_e32 v145, 0xffff0000, v116
	v_lshlrev_b32_e32 v146, 16, v117
	v_and_b32_e32 v147, 0xffff0000, v117
	v_pk_mul_f32 v[144:145], v[154:155], v[144:145] op_sel_hi:[0,1]
	v_pk_mul_f32 v[146:147], v[154:155], v[146:147] op_sel_hi:[0,1]
	v_pk_fma_f32 v[36:37], v[144:145], v[208:209], v[36:37]
	v_pk_fma_f32 v[38:39], v[146:147], v[210:211], v[38:39]
	v_pk_fma_f32 v[148:149], v[36:37], v[36:37], v[148:149]
	v_pk_fma_f32 v[150:151], v[38:39], v[38:39], v[150:151]
	v_cvt_pk_bf16_f32 v144, v36, v37
	v_cvt_pk_bf16_f32 v145, v38, v39
	global_store_dwordx2 v[84:85], v[144:145], off offset:-3072
	v_lshlrev_b32_e32 v130, 16, v102
	v_and_b32_e32 v131, 0xffff0000, v102
	v_lshlrev_b32_e32 v132, 16, v103
	v_and_b32_e32 v133, 0xffff0000, v103
	v_pk_mul_f32 v[130:131], v[152:153], v[130:131] op_sel_hi:[0,1]
	v_pk_mul_f32 v[132:133], v[152:153], v[132:133] op_sel_hi:[0,1]
	v_pk_fma_f32 v[8:9], v[130:131], v[212:213], v[8:9]
	v_pk_fma_f32 v[10:11], v[132:133], v[214:215], v[10:11]
	v_pk_fma_f32 v[94:95], v[8:9], v[8:9], v[94:95]
	v_pk_fma_f32 v[134:135], v[10:11], v[10:11], v[134:135]
	v_cvt_pk_bf16_f32 v130, v8, v9
	v_cvt_pk_bf16_f32 v131, v10, v11
	global_store_dwordx2 v[88:89], v[130:131], off offset:-2560
	v_lshlrev_b32_e32 v144, 16, v118
	v_and_b32_e32 v145, 0xffff0000, v118
	v_lshlrev_b32_e32 v146, 16, v119
	v_and_b32_e32 v147, 0xffff0000, v119
	v_pk_mul_f32 v[144:145], v[154:155], v[144:145] op_sel_hi:[0,1]
	v_pk_mul_f32 v[146:147], v[154:155], v[146:147] op_sel_hi:[0,1]
; __device__ __forceinline__ unsigned cvt_pk_bf16(float lo, float hi) { cvt_f32x2_t v = {lo, hi}; cvt_bf16x2_t b = __builtin_convertvector(v, cvt_bf16x2_t); return __builtin_bit_cast(unsigned, b); }
; __device__ __forceinline__ void rowpass_res(const Frame& F, const Params& p, const float* gpost, const float* gnext, bool first, bool last) {
;     ...
;         for (int u = 0; u < 2; ++u) { const int r = r0 + u; bf16* hb = HB + (size_t)r * D;
; #pragma unroll
;             for (int j = 0; j < 8; ++j) { const f32x4 g = *(const f32x4*)(gpost + 4 * F.lane + 256 * j);
;                 v[u][j] = hv[u][j] + v[u][j] * rs[u] * g;
;                 if (last) { if (r < MF) *(f32x4*)(p.out + (size_t)r * D + 4 * F.lane + 256 * j) = v[u][j]; }
;                 else { u32x2 w; w.x = cvt_pk_bf16(v[u][j].x, v[u][j].y); w.y = cvt_pk_bf16(v[u][j].z, v[u][j].w); *(u32x2*)(hb + 4 * F.lane + 256 * j) = w; }
;                 ss2[u] += (v[u][j].x * v[u][j].x + v[u][j].y * v[u][j].y) + (v[u][j].z * v[u][j].z + v[u][j].w * v[u][j].w); } }
	v_pk_fma_f32 v[40:41], v[144:145], v[212:213], v[40:41]
	v_pk_fma_f32 v[42:43], v[146:147], v[214:215], v[42:43]
	v_pk_fma_f32 v[148:149], v[40:41], v[40:41], v[148:149]
	v_pk_fma_f32 v[150:151], v[42:43], v[42:43], v[150:151]
	v_cvt_pk_bf16_f32 v144, v40, v41
	v_cvt_pk_bf16_f32 v145, v42, v43
	global_store_dwordx2 v[84:85], v[144:145], off offset:-2560
	v_lshlrev_b32_e32 v130, 16, v104
	v_and_b32_e32 v131, 0xffff0000, v104
	v_lshlrev_b32_e32 v132, 16, v105
	v_and_b32_e32 v133, 0xffff0000, v105
	v_pk_mul_f32 v[130:131], v[152:153], v[130:131] op_sel_hi:[0,1]
	v_pk_mul_f32 v[132:133], v[152:153], v[132:133] op_sel_hi:[0,1]
	v_pk_fma_f32 v[12:13], v[130:131], v[216:217], v[12:13]
	v_pk_fma_f32 v[14:15], v[132:133], v[218:219], v[14:15]
	v_pk_fma_f32 v[94:95], v[12:13], v[12:13], v[94:95]
	v_pk_fma_f32 v[134:135], v[14:15], v[14:15], v[134:135]
	v_cvt_pk_bf16_f32 v130, v12, v13
	v_cvt_pk_bf16_f32 v131, v14, v15
	global_store_dwordx2 v[88:89], v[130:131], off offset:-2048
	v_lshlrev_b32_e32 v144, 16, v120
	v_and_b32_e32 v145, 0xffff0000, v120
	v_lshlrev_b32_e32 v146, 16, v121
	v_and_b32_e32 v147, 0xffff0000, v121
	v_pk_mul_f32 v[144:145], v[154:155], v[144:145] op_sel_hi:[0,1]
	v_pk_mul_f32 v[146:147], v[154:155], v[146:147] op_sel_hi:[0,1]
	v_pk_fma_f32 v[44:45], v[144:145], v[216:217], v[44:45]
	v_pk_fma_f32 v[46:47], v[146:147], v[218:219], v[46:47]
	v_pk_fma_f32 v[148:149], v[44:45], v[44:45], v[148:149]
	v_pk_fma_f32 v[150:151], v[46:47], v[46:47], v[150:151]
	v_cvt_pk_bf16_f32 v144, v44, v45
	v_cvt_pk_bf16_f32 v145, v46, v47
	global_store_dwordx2 v[84:85], v[144:145], off offset:-2048
	v_lshlrev_b32_e32 v130, 16, v106
	v_and_b32_e32 v131, 0xffff0000, v106
	v_lshlrev_b32_e32 v132, 16, v107
	v_and_b32_e32 v133, 0xffff0000, v107
	v_pk_mul_f32 v[130:131], v[152:153], v[130:131] op_sel_hi:[0,1]
	v_pk_mul_f32 v[132:133], v[152:153], v[132:133] op_sel_hi:[0,1]
	v_pk_fma_f32 v[16:17], v[130:131], v[220:221], v[16:17]
	v_pk_fma_f32 v[18:19], v[132:133], v[222:223], v[18:19]
	v_pk_fma_f32 v[94:95], v[16:17], v[16:17], v[94:95]
	v_pk_fma_f32 v[134:135], v[18:19], v[18:19], v[134:135]
	v_cvt_pk_bf16_f32 v130, v16, v17
	v_cvt_pk_bf16_f32 v131, v18, v19
	global_store_dwordx2 v[88:89], v[130:131], off offset:-1536
	v_lshlrev_b32_e32 v144, 16, v122
	v_and_b32_e32 v145, 0xffff0000, v122
	v_lshlrev_b32_e32 v146, 16, v123
	v_and_b32_e32 v147, 0xffff0000, v123
	v_pk_mul_f32 v[144:145], v[154:155], v[144:145] op_sel_hi:[0,1]
	v_pk_mul_f32 v[146:147], v[154:155], v[146:147] op_sel_hi:[0,1]
	v_pk_fma_f32 v[48:49], v[144:145], v[220:221], v[48:49]
	v_pk_fma_f32 v[50:51], v[146:147], v[222:223], v[50:51]
	v_pk_fma_f32 v[148:149], v[48:49], v[48:49], v[148:149]
	v_pk_fma_f32 v[150:151], v[50:51], v[50:51], v[150:151]
	v_cvt_pk_bf16_f32 v144, v48, v49
	v_cvt_pk_bf16_f32 v145, v50, v51
	global_store_dwordx2 v[84:85], v[144:145], off offset:-1536
	v_lshlrev_b32_e32 v130, 16, v108
	v_and_b32_e32 v131, 0xffff0000, v108
	v_lshlrev_b32_e32 v132, 16, v109
	v_and_b32_e32 v133, 0xffff0000, v109
	v_pk_mul_f32 v[130:131], v[152:153], v[130:131] op_sel_hi:[0,1]
	v_pk_mul_f32 v[132:133], v[152:153], v[132:133] op_sel_hi:[0,1]
	v_pk_fma_f32 v[20:21], v[130:131], v[224:225], v[20:21]
	v_pk_fma_f32 v[22:23], v[132:133], v[226:227], v[22:23]
	v_pk_fma_f32 v[94:95], v[20:21], v[20:21], v[94:95]
	v_pk_fma_f32 v[134:135], v[22:23], v[22:23], v[134:135]
	v_cvt_pk_bf16_f32 v130, v20, v21
	v_cvt_pk_bf16_f32 v131, v22, v23
	global_store_dwordx2 v[88:89], v[130:131], off offset:-1024
	v_lshlrev_b32_e32 v144, 16, v124
	v_and_b32_e32 v145, 0xffff0000, v124
	v_lshlrev_b32_e32 v146, 16, v125
	v_and_b32_e32 v147, 0xffff0000, v125
	v_pk_mul_f32 v[144:145], v[154:155], v[144:145] op_sel_hi:[0,1]
	v_pk_mul_f32 v[146:147], v[154:155], v[146:147] op_sel_hi:[0,1]
	v_pk_fma_f32 v[52:53], v[144:145], v[224:225], v[52:53]
	v_pk_fma_f32 v[54:55], v[146:147], v[226:227], v[54:55]
	v_pk_fma_f32 v[148:149], v[52:53], v[52:53], v[148:149]
	v_pk_fma_f32 v[150:151], v[54:55], v[54:55], v[150:151]
	v_cvt_pk_bf16_f32 v144, v52, v53
	v_cvt_pk_bf16_f32 v145, v54, v55
	global_store_dwordx2 v[84:85], v[144:145], off offset:-1024
	v_lshlrev_b32_e32 v130, 16, v110
	v_and_b32_e32 v131, 0xffff0000, v110
	v_lshlrev_b32_e32 v132, 16, v111
	v_and_b32_e32 v133, 0xffff0000, v111
	v_pk_mul_f32 v[130:131], v[152:153], v[130:131] op_sel_hi:[0,1]
	v_pk_mul_f32 v[132:133], v[152:153], v[132:133] op_sel_hi:[0,1]
	v_pk_fma_f32 v[24:25], v[130:131], v[228:229], v[24:25]
	v_pk_fma_f32 v[26:27], v[132:133], v[230:231], v[26:27]
	v_pk_fma_f32 v[94:95], v[24:25], v[24:25], v[94:95]
	v_pk_fma_f32 v[134:135], v[26:27], v[26:27], v[134:135]
	v_cvt_pk_bf16_f32 v130, v24, v25
	v_cvt_pk_bf16_f32 v131, v26, v27
	global_store_dwordx2 v[88:89], v[130:131], off offset:-512
	v_lshlrev_b32_e32 v144, 16, v126
	v_and_b32_e32 v145, 0xffff0000, v126
	v_lshlrev_b32_e32 v146, 16, v127
	v_and_b32_e32 v147, 0xffff0000, v127
	v_pk_mul_f32 v[144:145], v[154:155], v[144:145] op_sel_hi:[0,1]
	v_pk_mul_f32 v[146:147], v[154:155], v[146:147] op_sel_hi:[0,1]
	v_pk_fma_f32 v[56:57], v[144:145], v[228:229], v[56:57]
	v_pk_fma_f32 v[58:59], v[146:147], v[230:231], v[58:59]
	v_pk_fma_f32 v[148:149], v[56:57], v[56:57], v[148:149]
	v_pk_fma_f32 v[150:151], v[58:59], v[58:59], v[150:151]
	v_cvt_pk_bf16_f32 v144, v56, v57
	v_cvt_pk_bf16_f32 v145, v58, v59
	global_store_dwordx2 v[84:85], v[144:145], off offset:-512
	v_lshlrev_b32_e32 v130, 16, v112
	v_and_b32_e32 v131, 0xffff0000, v112
	v_lshlrev_b32_e32 v132, 16, v113
	v_and_b32_e32 v133, 0xffff0000, v113
	v_pk_mul_f32 v[130:131], v[152:153], v[130:131] op_sel_hi:[0,1]
	v_pk_mul_f32 v[132:133], v[152:153], v[132:133] op_sel_hi:[0,1]
	v_pk_fma_f32 v[28:29], v[130:131], v[232:233], v[28:29]
	v_pk_fma_f32 v[30:31], v[132:133], v[234:235], v[30:31]
	v_pk_fma_f32 v[94:95], v[28:29], v[28:29], v[94:95]
	v_pk_fma_f32 v[134:135], v[30:31], v[30:31], v[134:135]
	v_cvt_pk_bf16_f32 v130, v28, v29
	v_cvt_pk_bf16_f32 v131, v30, v31
	global_store_dwordx2 v[88:89], v[130:131], off
	v_lshlrev_b32_e32 v144, 16, v128
	v_and_b32_e32 v145, 0xffff0000, v128
	v_lshlrev_b32_e32 v146, 16, v129
	v_and_b32_e32 v147, 0xffff0000, v129
	v_pk_mul_f32 v[144:145], v[154:155], v[144:145] op_sel_hi:[0,1]
	v_pk_mul_f32 v[146:147], v[154:155], v[146:147] op_sel_hi:[0,1]
	v_pk_fma_f32 v[60:61], v[144:145], v[232:233], v[60:61]
	v_pk_fma_f32 v[62:63], v[146:147], v[234:235], v[62:63]
	v_pk_fma_f32 v[148:149], v[60:61], v[60:61], v[148:149]
	v_pk_fma_f32 v[150:151], v[62:63], v[62:63], v[150:151]
	v_cvt_pk_bf16_f32 v144, v60, v61
	v_cvt_pk_bf16_f32 v145, v62, v63
	global_store_dwordx2 v[84:85], v[144:145], off
; __device__ __forceinline__ unsigned cvt_pk_bf16(float lo, float hi) { cvt_f32x2_t v = {lo, hi}; cvt_bf16x2_t b = __builtin_convertvector(v, cvt_bf16x2_t); return __builtin_bit_cast(unsigned, b); }
; __device__ __forceinline__ void rowpass_res(const Frame& F, const Params& p, const float* gpost, const float* gnext, bool first, bool last) {
;     ...
;         if (gnext) {
; #pragma unroll
;             for (int o = 1; o < 64; o <<= 1) { ss2[0] += __shfl_xor(ss2[0], o); ss2[1] += __shfl_xor(ss2[1], o); }
; #pragma unroll
;             for (int u = 0; u < 2; ++u) { const float rs2 = rsqrtf(ss2[u] * (1.f / D) + EPS);
; #pragma unroll
;                 for (int j = 0; j < 8; ++j) { const f32x4 g = *(const f32x4*)(gnext + 4 * F.lane + 256 * j);
;                     u32x2 w; w.x = cvt_pk_bf16(v[u][j].x * rs2 * g.x, v[u][j].y * rs2 * g.y); w.y = cvt_pk_bf16(v[u][j].z * rs2 * g.z, v[u][j].w * rs2 * g.w);
;                     *(u32x2*)(A + (size_t)(r0 + u) * D + 4 * F.lane + 256 * j) = w; } }
.Lrp9_out_done:
	s_cmp_lg_u64 s[66:67], 0
	s_cbranch_scc0 .LBB0_1203
	v_pk_add_f32 v[94:95], v[94:95], v[134:135]
	v_pk_add_f32 v[148:149], v[148:149], v[150:151]
	v_add_f32_e32 v152, v94, v95
	v_add_f32_e32 v154, v148, v149
	v_mov_b32_e32 v156, 0x358637bd
	s_nop 1
	v_add_f32_dpp v152, v152, v152 row_ror:8 row_mask:0xf bank_mask:0xf
	v_add_f32_dpp v154, v154, v154 row_ror:8 row_mask:0xf bank_mask:0xf
	s_nop 1
	v_add_f32_dpp v152, v152, v152 row_ror:4 row_mask:0xf bank_mask:0xf
	v_add_f32_dpp v154, v154, v154 row_ror:4 row_mask:0xf bank_mask:0xf
	s_nop 1
	v_add_f32_dpp v152, v152, v152 row_ror:2 row_mask:0xf bank_mask:0xf
	v_add_f32_dpp v154, v154, v154 row_ror:2 row_mask:0xf bank_mask:0xf
	s_nop 1
	v_add_f32_dpp v152, v152, v152 row_ror:1 row_mask:0xf bank_mask:0xf
	v_add_f32_dpp v154, v154, v154 row_ror:1 row_mask:0xf bank_mask:0xf
	s_nop 1
	v_readlane_b32 s0, v152, 0
	v_readlane_b32 s1, v152, 16
	v_readlane_b32 s2, v152, 32
	v_readlane_b32 s3, v152, 48
	v_readlane_b32 s4, v154, 0
	v_readlane_b32 s5, v154, 16
	v_readlane_b32 s8, v154, 32
	v_readlane_b32 s9, v154, 48
	s_nop 1
	v_mov_b32_e32 v152, s0
	v_mov_b32_e32 v154, s4
	v_add_f32_e32 v152, s1, v152
	v_add_f32_e32 v154, s5, v154
	v_add_f32_e32 v152, s2, v152
	v_add_f32_e32 v154, s8, v154
	v_add_f32_e32 v152, s3, v152
	v_add_f32_e32 v154, s9, v154
	v_fmamk_f32 v152, v152, 0x3a000000, v156
	v_fmamk_f32 v154, v154, 0x3a000000, v156
	v_rsq_f32_e32 v152, v152
	v_rsq_f32_e32 v154, v154
	s_nop 0
	v_add_co_u32_e32 v90, vcc, 0xd1480000, v88
	s_nop 1
	v_addc_co_u32_e32 v91, vcc, -1, v89, vcc
	v_add_co_u32_e32 v92, vcc, 0xd1480000, v84
	s_nop 1
	v_addc_co_u32_e32 v93, vcc, -1, v85, vcc
	v_pk_mul_f32 v[130:131], v[152:153], v[0:1] op_sel_hi:[0,1]
	v_pk_mul_f32 v[132:133], v[152:153], v[2:3] op_sel_hi:[0,1]
	v_pk_mul_f32 v[130:131], v[130:131], v[236:237]
	v_pk_mul_f32 v[132:133], v[132:133], v[238:239]
	v_cvt_pk_bf16_f32 v130, v130, v131
	v_cvt_pk_bf16_f32 v131, v132, v133
	global_store_dwordx2 v[90:91], v[130:131], off offset:-3584
	v_pk_mul_f32 v[144:145], v[154:155], v[32:33] op_sel_hi:[0,1]
	v_pk_mul_f32 v[146:147], v[154:155], v[34:35] op_sel_hi:[0,1]
	v_pk_mul_f32 v[144:145], v[144:145], v[236:237]
	v_pk_mul_f32 v[146:147], v[146:147], v[238:239]
	v_cvt_pk_bf16_f32 v144, v144, v145
	v_cvt_pk_bf16_f32 v145, v146, v147
	global_store_dwordx2 v[92:93], v[144:145], off offset:-3584
	v_pk_mul_f32 v[130:131], v[152:153], v[4:5] op_sel_hi:[0,1]
	v_pk_mul_f32 v[132:133], v[152:153], v[6:7] op_sel_hi:[0,1]
	v_pk_mul_f32 v[130:131], v[130:131], v[240:241]
	v_pk_mul_f32 v[132:133], v[132:133], v[242:243]
	v_cvt_pk_bf16_f32 v130, v130, v131
	v_cvt_pk_bf16_f32 v131, v132, v133
	global_store_dwordx2 v[90:91], v[130:131], off offset:-3072
	v_pk_mul_f32 v[144:145], v[154:155], v[36:37] op_sel_hi:[0,1]
	v_pk_mul_f32 v[146:147], v[154:155], v[38:39] op_sel_hi:[0,1]
	v_pk_mul_f32 v[144:145], v[144:145], v[240:241]
	v_pk_mul_f32 v[146:147], v[146:147], v[242:243]
	v_cvt_pk_bf16_f32 v144, v144, v145
	v_cvt_pk_bf16_f32 v145, v146, v147
	global_store_dwordx2 v[92:93], v[144:145], off offset:-3072
	v_pk_mul_f32 v[130:131], v[152:153], v[8:9] op_sel_hi:[0,1]
	v_pk_mul_f32 v[132:133], v[152:153], v[10:11] op_sel_hi:[0,1]
	v_pk_mul_f32 v[130:131], v[130:131], v[244:245]
	v_pk_mul_f32 v[132:133], v[132:133], v[246:247]
	v_cvt_pk_bf16_f32 v130, v130, v131
	v_cvt_pk_bf16_f32 v131, v132, v133
	global_store_dwordx2 v[90:91], v[130:131], off offset:-2560
	v_pk_mul_f32 v[144:145], v[154:155], v[40:41] op_sel_hi:[0,1]
	v_pk_mul_f32 v[146:147], v[154:155], v[42:43] op_sel_hi:[0,1]
	v_pk_mul_f32 v[144:145], v[144:145], v[244:245]
	v_pk_mul_f32 v[146:147], v[146:147], v[246:247]
	v_cvt_pk_bf16_f32 v144, v144, v145
; __device__ __forceinline__ unsigned cvt_pk_bf16(float lo, float hi) { cvt_f32x2_t v = {lo, hi}; cvt_bf16x2_t b = __builtin_convertvector(v, cvt_bf16x2_t); return __builtin_bit_cast(unsigned, b); }
; __device__ __forceinline__ void rowpass_res(const Frame& F, const Params& p, const float* gpost, const float* gnext, bool first, bool last) {
;     ...
;             for (int u = 0; u < 2; ++u) { const float rs2 = rsqrtf(ss2[u] * (1.f / D) + EPS);
; #pragma unroll
;                 for (int j = 0; j < 8; ++j) { const f32x4 g = *(const f32x4*)(gnext + 4 * F.lane + 256 * j);
;                     u32x2 w; w.x = cvt_pk_bf16(v[u][j].x * rs2 * g.x, v[u][j].y * rs2 * g.y); w.y = cvt_pk_bf16(v[u][j].z * rs2 * g.z, v[u][j].w * rs2 * g.w);
;                     *(u32x2*)(A + (size_t)(r0 + u) * D + 4 * F.lane + 256 * j) = w; } }
	v_cvt_pk_bf16_f32 v145, v146, v147
	global_store_dwordx2 v[92:93], v[144:145], off offset:-2560
	v_pk_mul_f32 v[130:131], v[152:153], v[12:13] op_sel_hi:[0,1]
	v_pk_mul_f32 v[132:133], v[152:153], v[14:15] op_sel_hi:[0,1]
	v_pk_mul_f32 v[130:131], v[130:131], v[248:249]
	v_pk_mul_f32 v[132:133], v[132:133], v[250:251]
	v_cvt_pk_bf16_f32 v130, v130, v131
	v_cvt_pk_bf16_f32 v131, v132, v133
	global_store_dwordx2 v[90:91], v[130:131], off offset:-2048
	v_pk_mul_f32 v[144:145], v[154:155], v[44:45] op_sel_hi:[0,1]
	v_pk_mul_f32 v[146:147], v[154:155], v[46:47] op_sel_hi:[0,1]
	v_pk_mul_f32 v[144:145], v[144:145], v[248:249]
	v_pk_mul_f32 v[146:147], v[146:147], v[250:251]
	v_cvt_pk_bf16_f32 v144, v144, v145
	v_cvt_pk_bf16_f32 v145, v146, v147
	global_store_dwordx2 v[92:93], v[144:145], off offset:-2048
	v_pk_mul_f32 v[130:131], v[152:153], v[16:17] op_sel_hi:[0,1]
	v_pk_mul_f32 v[132:133], v[152:153], v[18:19] op_sel_hi:[0,1]
	v_pk_mul_f32 v[130:131], v[130:131], v[186:187]
	v_pk_mul_f32 v[132:133], v[132:133], v[188:189]
	v_cvt_pk_bf16_f32 v130, v130, v131
	v_cvt_pk_bf16_f32 v131, v132, v133
	global_store_dwordx2 v[90:91], v[130:131], off offset:-1536
	v_pk_mul_f32 v[144:145], v[154:155], v[48:49] op_sel_hi:[0,1]
	v_pk_mul_f32 v[146:147], v[154:155], v[50:51] op_sel_hi:[0,1]
	v_pk_mul_f32 v[144:145], v[144:145], v[186:187]
	v_pk_mul_f32 v[146:147], v[146:147], v[188:189]
	v_cvt_pk_bf16_f32 v144, v144, v145
	v_cvt_pk_bf16_f32 v145, v146, v147
	global_store_dwordx2 v[92:93], v[144:145], off offset:-1536
	v_pk_mul_f32 v[130:131], v[152:153], v[20:21] op_sel_hi:[0,1]
	v_pk_mul_f32 v[132:133], v[152:153], v[22:23] op_sel_hi:[0,1]
	v_pk_mul_f32 v[130:131], v[130:131], v[190:191]
	v_pk_mul_f32 v[132:133], v[132:133], v[192:193]
	v_cvt_pk_bf16_f32 v130, v130, v131
	v_cvt_pk_bf16_f32 v131, v132, v133
	global_store_dwordx2 v[90:91], v[130:131], off offset:-1024
	v_pk_mul_f32 v[144:145], v[154:155], v[52:53] op_sel_hi:[0,1]
	v_pk_mul_f32 v[146:147], v[154:155], v[54:55] op_sel_hi:[0,1]
	v_pk_mul_f32 v[144:145], v[144:145], v[190:191]
	v_pk_mul_f32 v[146:147], v[146:147], v[192:193]
	v_cvt_pk_bf16_f32 v144, v144, v145
	v_cvt_pk_bf16_f32 v145, v146, v147
	global_store_dwordx2 v[92:93], v[144:145], off offset:-1024
	v_pk_mul_f32 v[130:131], v[152:153], v[24:25] op_sel_hi:[0,1]
	v_pk_mul_f32 v[132:133], v[152:153], v[26:27] op_sel_hi:[0,1]
	v_pk_mul_f32 v[130:131], v[130:131], v[194:195]
	v_pk_mul_f32 v[132:133], v[132:133], v[196:197]
	v_cvt_pk_bf16_f32 v130, v130, v131
	v_cvt_pk_bf16_f32 v131, v132, v133
	global_store_dwordx2 v[90:91], v[130:131], off offset:-512
	v_pk_mul_f32 v[144:145], v[154:155], v[56:57] op_sel_hi:[0,1]
	v_pk_mul_f32 v[146:147], v[154:155], v[58:59] op_sel_hi:[0,1]
	v_pk_mul_f32 v[144:145], v[144:145], v[194:195]
	v_pk_mul_f32 v[146:147], v[146:147], v[196:197]
	v_cvt_pk_bf16_f32 v144, v144, v145
	v_cvt_pk_bf16_f32 v145, v146, v147
	global_store_dwordx2 v[92:93], v[144:145], off offset:-512
	v_pk_mul_f32 v[130:131], v[152:153], v[28:29] op_sel_hi:[0,1]
	v_pk_mul_f32 v[132:133], v[152:153], v[30:31] op_sel_hi:[0,1]
	v_pk_mul_f32 v[130:131], v[130:131], v[198:199]
	v_pk_mul_f32 v[132:133], v[132:133], v[200:201]
	v_cvt_pk_bf16_f32 v130, v130, v131
	v_cvt_pk_bf16_f32 v131, v132, v133
	global_store_dwordx2 v[90:91], v[130:131], off
	v_pk_mul_f32 v[144:145], v[154:155], v[60:61] op_sel_hi:[0,1]
	v_pk_mul_f32 v[146:147], v[154:155], v[62:63] op_sel_hi:[0,1]
	v_pk_mul_f32 v[144:145], v[144:145], v[198:199]
	v_pk_mul_f32 v[146:147], v[146:147], v[200:201]
	v_cvt_pk_bf16_f32 v144, v144, v145
	v_cvt_pk_bf16_f32 v145, v146, v147
	global_store_dwordx2 v[92:93], v[144:145], off
	s_branch .LBB0_1203
